# v082 plus L2 warm-up of the next item's K/V/Q lines in the sliding-window attention phase
# speedup vs baseline: 1.0024x; 1.0024x over previous
; __device__ __forceinline__ int ptid_(int wave) { int l_; asm volatile("v_mbcnt_lo_u32_b32 %0, -1, 0\n\tv_mbcnt_hi_u32_b32 %0, -1, %0" : "=v"(l_)); return (wave << 6) | l_; }
; __device__ void swa_item(const Params& p, int item) {
;     ...
;   bfu* buf = (bfu*)(p.ws + R_OFF);
;   const int pat = item >> 10; const int rem = item & 1023;
;   const int b = rem >> 7, head = (rem >> 5) & 3, sub = rem & 31;
;   const int dil = (pat == 0) ? 1 : (pat == 1 ? 4 : 16);
;   const int nqb = 32 / dil;
;   const int r = sub / nqb, qb = sub % nqb;
;   int tid = ptid_(p.tid); asm volatile("" : "+v"(tid)); const int w = tid >> 6, lane = tid & 63, c = lane & 15, q = lane >> 4;
;   bfu* Vt = (bfu*)smem;
;   bfu* Ks = Vt + 128 * 280;
;   bfu* Pl = Ks + w * (16 * 168);
;   const long rowb = (long)b * TSEQ;
;   const int qcol = pat * 512 + head * 128, kcol = 1536 + qcol, vcol = 3072 + qcol;
;   __syncthreads();
;   _Pragma("unroll") for (int i = 0; i < 4; ++i) {
;     int co = tid + 512 * i; int c8 = co & 15, kp = co >> 4;
;     int j0 = qb * 128 - 128 + 2 * kp;
;     const int j0c = (j0 >= 0) ? j0 : 0;
;     bf16x8 v0 = *(const bf16x8*)(buf + (rowb + (long)j0c * dil + r) * 4608 + vcol + c8 * 8);
;     bf16x8 v1 = *(const bf16x8*)(buf + (rowb + (long)(j0c + 1) * dil + r) * 4608 + vcol + c8 * 8);
;     if (j0 < 0) { v0 = (bf16x8){0, 0, 0, 0, 0, 0, 0, 0}; v1 = v0; }
;     const int chs = ((kp >> 2) ^ c8) * 8 + ((2 * kp) & 7);
;     _Pragma("unroll") for (int e = 0; e < 8; ++e)
;       *(unsigned*)(Vt + (c8 * 8 + e) * 280 + chs) = (unsigned)(bfu)v0[e] | ((unsigned)(bfu)v1[e] << 16);
;   }
;   _Pragma("unroll") for (int i = 0; i < 8; ++i) {
;     int co = tid + 512 * i; int c8 = co & 15, kj = co >> 4;
;     int j = qb * 128 - 128 + kj; j = (j >= 0) ? j : 0;
;     *(bf16x8*)(Ks + kj * 136 + c8 * 8) = *(const bf16x8*)(buf + (rowb + (long)j * dil + r) * 4608 + kcol + c8 * 8);
;   }
.LBB0_102:
	s_cmpk_gt_i32 s21, 0xbff
	s_cbranch_scc1 .LBB0_113
	s_ashr_i32 s88, s21, 10
	s_bfe_u32 s23, s21, 0x20005
	s_and_b32 s0, s21, 31
	s_cmp_eq_u32 s88, 1
	s_cselect_b32 s1, 2, 4
	s_cmpk_gt_u32 s21, 0x3ff
	s_cselect_b32 s22, s1, 0
	s_lshr_b32 s1, 32, s22
	s_sub_i32 s2, 5, s22
	s_add_i32 s1, s1, -1
	s_lshr_b32 s2, s0, s2
	s_and_b32 s34, s1, s0
	s_lshl_b32 s0, s21, 5
	s_and_b32 s1, s0, 0x7000
	s_lshl_b32 s0, s88, 9
	s_lshl_b32 s3, s23, 7
	s_or_b32 s0, s3, s0
	v_readlane_b32 s18, v254, 13
	s_lshl_b32 s35, s34, 7
	s_or_b32 s18, s2, s1
	s_ashr_i32 s1, s0, 31
	v_mbcnt_lo_u32_b32 v0, -1, 0
	v_mbcnt_hi_u32_b32 v0, -1, v0
	s_add_i32 s12, s35, 0xffffff80
	v_or_b32_e32 v50, s33, v0
	s_lshl_b64 s[2:3], s[0:1], 1
	s_add_u32 s52, s16, s2
	v_and_b32_e32 v55, 15, v50
	s_addc_u32 s53, s17, s3
	v_lshlrev_b32_e32 v0, 4, v55
	v_ashrrev_i32_e32 v13, 3, v50
	s_waitcnt lgkmcnt(0)
	v_lshl_add_u64 v[2:3], s[52:53], 0, v[0:1]
	v_and_b32_e32 v0, -2, v13
	v_add_u32_e32 v14, s12, v0
	s_mov_b64 s[2:3], 0x1800
	v_max_i32_e32 v0, 0, v14
	v_lshl_add_u64 v[10:11], v[2:3], 0, s[2:3]
	v_lshlrev_b64 v[2:3], s22, v[0:1]
	v_or_b32_e32 v0, 1, v0
	v_readlane_b32 s19, v254, 14
	v_lshlrev_b64 v[6:7], s22, v[0:1]
	s_nop 0
	v_lshl_add_u64 v[2:3], v[2:3], 0, s[18:19]
	v_lshl_add_u64 v[6:7], v[6:7], 0, s[18:19]
	v_mad_u64_u32 v[4:5], s[2:3], v2, s89, v[10:11]
	v_mad_u64_u32 v[8:9], s[2:3], v6, s89, v[10:11]
	v_mad_u32_u24 v5, v3, s89, v5
	v_mad_u32_u24 v9, v7, s89, v9
	s_barrier
	v_lshlrev_b32_e32 v140, 4, v55
	v_mov_b32_e32 v141, 0
	v_lshl_add_u64 v[140:141], s[52:53], 0, v[140:141]
	s_mov_b64 s[2:3], 0x1800
	v_lshl_add_u64 v[142:143], v[140:141], 0, s[2:3]
	v_lshrrev_b32_e32 v144, 4, v50
	v_lshl_add_u32 v145, v144, 1, s12
	v_max_i32_e32 v146, 0, v145
	v_lshlrev_b32_e32 v147, s22, v146
	v_add_u32_e32 v147, s18, v147
	v_mad_u64_u32 v[148:149], vcc, v147, s89, v[142:143]
	global_load_dwordx4 v[76:79], v[148:149], off
	v_or_b32_e32 v146, 1, v146
	v_lshlrev_b32_e32 v147, s22, v146
	v_add_u32_e32 v147, s18, v147
	v_mad_u64_u32 v[148:149], vcc, v147, s89, v[142:143]
	global_load_dwordx4 v[80:83], v[148:149], off
	v_add_u32_e32 v146, 64, v145
	v_max_i32_e32 v146, 0, v146
	v_lshlrev_b32_e32 v147, s22, v146
	v_add_u32_e32 v147, s18, v147
	v_mad_u64_u32 v[148:149], vcc, v147, s89, v[142:143]
	global_load_dwordx4 v[84:87], v[148:149], off
	v_or_b32_e32 v146, 1, v146
	v_lshlrev_b32_e32 v147, s22, v146
	v_add_u32_e32 v147, s18, v147
	v_mad_u64_u32 v[148:149], vcc, v147, s89, v[142:143]
	global_load_dwordx4 v[88:91], v[148:149], off
	v_add_u32_e32 v146, 128, v145
	v_max_i32_e32 v146, 0, v146
	v_lshlrev_b32_e32 v147, s22, v146
	v_add_u32_e32 v147, s18, v147
	v_mad_u64_u32 v[148:149], vcc, v147, s89, v[142:143]
	global_load_dwordx4 v[92:95], v[148:149], off
	v_or_b32_e32 v146, 1, v146
	v_lshlrev_b32_e32 v147, s22, v146
	v_add_u32_e32 v147, s18, v147
	v_mad_u64_u32 v[148:149], vcc, v147, s89, v[142:143]
	global_load_dwordx4 v[96:99], v[148:149], off
	v_add_u32_e32 v146, 192, v145
	v_max_i32_e32 v146, 0, v146
	v_lshlrev_b32_e32 v147, s22, v146
	v_add_u32_e32 v147, s18, v147
	v_mad_u64_u32 v[148:149], vcc, v147, s89, v[142:143]
	global_load_dwordx4 v[100:103], v[148:149], off
	v_or_b32_e32 v146, 1, v146
	v_lshlrev_b32_e32 v147, s22, v146
	v_add_u32_e32 v147, s18, v147
	v_mad_u64_u32 v[148:149], vcc, v147, s89, v[142:143]
	global_load_dwordx4 v[104:107], v[148:149], off
	v_add_u32_e32 v145, s12, v144
	v_max_i32_e32 v146, 0, v145
	v_lshlrev_b32_e32 v147, s22, v146
	v_add_u32_e32 v147, s18, v147
	v_mad_u64_u32 v[148:149], vcc, v147, s89, v[140:141]
	global_load_dwordx4 v[108:111], v[148:149], off offset:3072
	v_add_u32_e32 v146, 32, v145
	v_max_i32_e32 v146, 0, v146
	v_lshlrev_b32_e32 v147, s22, v146
	v_add_u32_e32 v147, s18, v147
	v_mad_u64_u32 v[148:149], vcc, v147, s89, v[140:141]
	global_load_dwordx4 v[112:115], v[148:149], off offset:3072
	v_add_u32_e32 v146, 64, v145
	v_max_i32_e32 v146, 0, v146
	v_lshlrev_b32_e32 v147, s22, v146
	v_add_u32_e32 v147, s18, v147
	v_mad_u64_u32 v[148:149], vcc, v147, s89, v[140:141]
	global_load_dwordx4 v[116:119], v[148:149], off offset:3072
	v_add_u32_e32 v146, 96, v145
	v_max_i32_e32 v146, 0, v146
	v_lshlrev_b32_e32 v147, s22, v146
	v_add_u32_e32 v147, s18, v147
	v_mad_u64_u32 v[148:149], vcc, v147, s89, v[140:141]
	global_load_dwordx4 v[120:123], v[148:149], off offset:3072
	v_add_u32_e32 v146, 128, v145
	v_max_i32_e32 v146, 0, v146
	v_lshlrev_b32_e32 v147, s22, v146
	v_add_u32_e32 v147, s18, v147
	v_mad_u64_u32 v[148:149], vcc, v147, s89, v[140:141]
	global_load_dwordx4 v[124:127], v[148:149], off offset:3072
	v_add_u32_e32 v146, 160, v145
	v_max_i32_e32 v146, 0, v146
	v_lshlrev_b32_e32 v147, s22, v146
	v_add_u32_e32 v147, s18, v147
	v_mad_u64_u32 v[148:149], vcc, v147, s89, v[140:141]
	global_load_dwordx4 v[128:131], v[148:149], off offset:3072
	v_add_u32_e32 v146, 192, v145
	v_max_i32_e32 v146, 0, v146
	v_lshlrev_b32_e32 v147, s22, v146
	v_add_u32_e32 v147, s18, v147
	v_mad_u64_u32 v[148:149], vcc, v147, s89, v[140:141]
	global_load_dwordx4 v[132:135], v[148:149], off offset:3072
	v_add_u32_e32 v146, 224, v145
	v_max_i32_e32 v146, 0, v146
	v_lshlrev_b32_e32 v147, s22, v146
	v_add_u32_e32 v147, s18, v147
	v_mad_u64_u32 v[148:149], vcc, v147, s89, v[140:141]
	global_load_dwordx4 v[136:139], v[148:149], off offset:3072
	v_mov_b32_e32 v243, s18
	v_lshrrev_b32_e32 v243, 12, v243
	v_add_u32_e32 v243, 2, v243
	v_lshrrev_b32_e32 v243, 3, v243
	v_sub_u32_e32 v243, 1, v243
	v_lshlrev_b32_e32 v243, 13, v243
	v_add_u32_e32 v243, s18, v243
	v_lshrrev_b32_e32 v244, 1, v50
	v_and_b32_e32 v245, 1, v50
	v_add_u32_e32 v246, s12, v244
	v_max_i32_e32 v246, 0, v246
	v_lshlrev_b32_e32 v246, s22, v246
	v_add_u32_e32 v246, v243, v246
	v_mul_u32_u24_e32 v246, 0x2400, v246
	v_lshl_add_u32 v246, v245, 7, v246
	v_add_u32_e32 v240, 0xc00, v246
	v_add_u32_e32 v241, 0x1800, v246
	v_and_b32_e32 v244, 0x7f, v244
	v_add_u32_e32 v244, s35, v244
	v_lshlrev_b32_e32 v244, s22, v244
	v_add_u32_e32 v244, v243, v244
	v_mul_u32_u24_e32 v244, 0x2400, v244
	v_lshl_add_u32 v242, v245, 7, v244
	s_waitcnt vmcnt(14)
; __device__ void swa_item(const Params& p, int item) {
;     ...
;   _Pragma("unroll") for (int i = 0; i < 4; ++i) {
;     int co = tid + 512 * i; int c8 = co & 15, kp = co >> 4;
;     int j0 = qb * 128 - 128 + 2 * kp;
;     const int j0c = (j0 >= 0) ? j0 : 0;
;     bf16x8 v0 = *(const bf16x8*)(buf + (rowb + (long)j0c * dil + r) * 4608 + vcol + c8 * 8);
;     bf16x8 v1 = *(const bf16x8*)(buf + (rowb + (long)(j0c + 1) * dil + r) * 4608 + vcol + c8 * 8);
;     if (j0 < 0) { v0 = (bf16x8){0, 0, 0, 0, 0, 0, 0, 0}; v1 = v0; }
;     const int chs = ((kp >> 2) ^ c8) * 8 + ((2 * kp) & 7);
;     _Pragma("unroll") for (int e = 0; e < 8; ++e)
;       *(unsigned*)(Vt + (c8 * 8 + e) * 280 + chs) = (unsigned)(bfu)v0[e] | ((unsigned)(bfu)v1[e] << 16);
;   }
	v_mov_b64_e32 v[2:3], v[76:77]
	v_mov_b64_e32 v[4:5], v[78:79]
	v_ashrrev_i32_e32 v12, 6, v50
	v_mov_b64_e32 v[6:7], v[80:81]
	v_mov_b64_e32 v[8:9], v[82:83]
	v_cmp_gt_i32_e32 vcc, 0, v14
	v_lshlrev_b32_e32 v13, 1, v13
	v_and_b32_e32 v14, 12, v13
	s_mov_b32 s13, 0x1000504
	v_mul_u32_u24_e32 v13, 0x1180, v55
	s_mov_b32 s14, 0x3020706
	v_add_u32_e32 v51, 0x200, v50
	v_cndmask_b32_e64 v2, v2, 0, vcc
	v_cndmask_b32_e64 v3, v3, 0, vcc
	v_cndmask_b32_e64 v0, v9, 0, vcc
	v_bitop3_b32 v9, v12, v50, 15 bitop3:0x78
	v_cndmask_b32_e64 v6, v6, 0, vcc
	v_lshl_add_u32 v9, v9, 4, 0
	v_cndmask_b32_e64 v7, v7, 0, vcc
	v_perm_b32 v15, v2, v6, s13
	v_add3_u32 v9, v9, v14, v13
	v_perm_b32 v2, v2, v6, s14
	v_cndmask_b32_e64 v8, v8, 0, vcc
	v_cndmask_b32_e64 v4, v4, 0, vcc
	ds_write2_b32 v9, v15, v2 offset1:140
	v_perm_b32 v2, v3, v7, s13
	v_perm_b32 v3, v3, v7, s14
	v_add_u32_e32 v6, 0x400, v9
	v_cndmask_b32_e64 v5, v5, 0, vcc
	ds_write2_b32 v6, v2, v3 offset0:24 offset1:164
	v_perm_b32 v2, v4, v8, s13
	v_perm_b32 v3, v4, v8, s14
	v_add_u32_e32 v4, 0x800, v9
	ds_write2_b32 v4, v2, v3 offset0:48 offset1:188
	v_perm_b32 v2, v5, v0, s13
	v_perm_b32 v0, v5, v0, s14
	v_add_u32_e32 v3, 0xc00, v9
	v_ashrrev_i32_e32 v14, 3, v51
	ds_write2_b32 v3, v2, v0 offset0:72 offset1:212
	v_and_b32_e32 v0, -2, v14
	v_add_u32_e32 v15, s12, v0
	v_max_i32_e32 v0, 0, v15
	v_lshlrev_b64 v[2:3], s22, v[0:1]
	v_or_b32_e32 v0, 1, v0
	v_lshlrev_b64 v[6:7], s22, v[0:1]
	v_lshl_add_u64 v[2:3], v[2:3], 0, s[18:19]
	v_lshl_add_u64 v[6:7], v[6:7], 0, s[18:19]
	v_mad_u64_u32 v[4:5], s[2:3], v2, s89, v[10:11]
	v_mad_u64_u32 v[8:9], s[2:3], v6, s89, v[10:11]
	v_mad_u32_u24 v5, v3, s89, v5
	v_mad_u32_u24 v9, v7, s89, v9
	s_waitcnt vmcnt(12)
	v_mov_b64_e32 v[2:3], v[84:85]
	v_mov_b64_e32 v[4:5], v[86:87]
	v_cmp_gt_i32_e32 vcc, 0, v15
	v_mov_b64_e32 v[6:7], v[88:89]
	v_mov_b64_e32 v[8:9], v[90:91]
	v_lshlrev_b32_e32 v14, 1, v14
	v_and_b32_e32 v14, 12, v14
	v_cndmask_b32_e64 v2, v2, 0, vcc
	v_cndmask_b32_e64 v3, v3, 0, vcc
	v_cndmask_b32_e64 v0, v9, 0, vcc
	v_ashrrev_i32_e32 v9, 6, v51
	v_bitop3_b32 v9, v9, v50, 15 bitop3:0x78
	v_cndmask_b32_e64 v6, v6, 0, vcc
	v_lshl_add_u32 v9, v9, 4, 0
	v_cndmask_b32_e64 v7, v7, 0, vcc
	v_perm_b32 v15, v2, v6, s13
	v_add3_u32 v9, v9, v14, v13
	v_perm_b32 v2, v2, v6, s14
	v_cndmask_b32_e64 v8, v8, 0, vcc
	v_cndmask_b32_e64 v4, v4, 0, vcc
	ds_write2_b32 v9, v15, v2 offset1:140
	v_perm_b32 v2, v3, v7, s13
	v_perm_b32 v3, v3, v7, s14
	v_add_u32_e32 v6, 0x400, v9
	v_cndmask_b32_e64 v5, v5, 0, vcc
	ds_write2_b32 v6, v2, v3 offset0:24 offset1:164
	v_perm_b32 v2, v4, v8, s13
	v_perm_b32 v3, v4, v8, s14
	v_add_u32_e32 v4, 0x800, v9
	v_add_u32_e32 v14, 0x400, v50
	ds_write2_b32 v4, v2, v3 offset0:48 offset1:188
	v_perm_b32 v2, v5, v0, s13
	v_perm_b32 v0, v5, v0, s14
	v_add_u32_e32 v3, 0xc00, v9
	v_ashrrev_i32_e32 v15, 3, v14
	ds_write2_b32 v3, v2, v0 offset0:72 offset1:212
	v_and_b32_e32 v0, -2, v15
	v_add_u32_e32 v16, s12, v0
	v_max_i32_e32 v0, 0, v16
	v_lshlrev_b64 v[2:3], s22, v[0:1]
	v_or_b32_e32 v0, 1, v0
	v_lshlrev_b64 v[6:7], s22, v[0:1]
	v_lshl_add_u64 v[2:3], v[2:3], 0, s[18:19]
	v_lshl_add_u64 v[6:7], v[6:7], 0, s[18:19]
	v_mad_u64_u32 v[4:5], s[2:3], v2, s89, v[10:11]
	v_mad_u64_u32 v[8:9], s[2:3], v6, s89, v[10:11]
	v_mad_u32_u24 v5, v3, s89, v5
	v_mad_u32_u24 v9, v7, s89, v9
	s_waitcnt vmcnt(10)
	v_mov_b64_e32 v[2:3], v[92:93]
	v_mov_b64_e32 v[4:5], v[94:95]
	v_cmp_gt_i32_e32 vcc, 0, v16
	v_mov_b64_e32 v[6:7], v[96:97]
	v_mov_b64_e32 v[8:9], v[98:99]
	v_lshlrev_b32_e32 v15, 1, v15
	v_and_b32_e32 v15, 12, v15
	v_cndmask_b32_e64 v2, v2, 0, vcc
	v_cndmask_b32_e64 v3, v3, 0, vcc
	v_cndmask_b32_e64 v0, v9, 0, vcc
	v_ashrrev_i32_e32 v9, 6, v14
	v_bitop3_b32 v9, v9, v50, 15 bitop3:0x78
	v_cndmask_b32_e64 v6, v6, 0, vcc
	v_lshl_add_u32 v9, v9, 4, 0
	v_cndmask_b32_e64 v7, v7, 0, vcc
	v_perm_b32 v16, v2, v6, s13
	v_add3_u32 v9, v9, v15, v13
	v_perm_b32 v2, v2, v6, s14
	v_cndmask_b32_e64 v8, v8, 0, vcc
	v_cndmask_b32_e64 v4, v4, 0, vcc
	ds_write2_b32 v9, v16, v2 offset1:140
	v_perm_b32 v2, v3, v7, s13
	v_perm_b32 v3, v3, v7, s14
	v_add_u32_e32 v6, 0x400, v9
	v_cndmask_b32_e64 v5, v5, 0, vcc
	ds_write2_b32 v6, v2, v3 offset0:24 offset1:164
	v_perm_b32 v2, v4, v8, s13
	v_perm_b32 v3, v4, v8, s14
	v_add_u32_e32 v4, 0x800, v9
	v_add_u32_e32 v15, 0x600, v50
	ds_write2_b32 v4, v2, v3 offset0:48 offset1:188
	v_perm_b32 v2, v5, v0, s13
	v_perm_b32 v0, v5, v0, s14
	v_add_u32_e32 v3, 0xc00, v9
	v_ashrrev_i32_e32 v16, 3, v15
	ds_write2_b32 v3, v2, v0 offset0:72 offset1:212
	v_and_b32_e32 v0, -2, v16
	v_add_u32_e32 v17, s12, v0
	v_max_i32_e32 v0, 0, v17
	v_lshlrev_b64 v[2:3], s22, v[0:1]
	v_or_b32_e32 v0, 1, v0
	v_lshlrev_b64 v[6:7], s22, v[0:1]
	v_lshl_add_u64 v[2:3], v[2:3], 0, s[18:19]
	v_lshl_add_u64 v[6:7], v[6:7], 0, s[18:19]
	v_mad_u64_u32 v[4:5], s[2:3], v2, s89, v[10:11]
	v_mad_u64_u32 v[8:9], s[2:3], v6, s89, v[10:11]
	v_mad_u32_u24 v5, v3, s89, v5
	v_mad_u32_u24 v9, v7, s89, v9
	s_waitcnt vmcnt(8)
; __device__ void swa_item(const Params& p, int item) {
;     ...
;   _Pragma("unroll") for (int i = 0; i < 8; ++i) {
;     int co = tid + 512 * i; int c8 = co & 15, kj = co >> 4;
;     int j = qb * 128 - 128 + kj; j = (j >= 0) ? j : 0;
;     *(bf16x8*)(Ks + kj * 136 + c8 * 8) = *(const bf16x8*)(buf + (rowb + (long)j * dil + r) * 4608 + kcol + c8 * 8);
;   }
;   for (int i = tid; i < 128 * 12; i += NTHR) { int dv = i / 12, k2 = i % 12; *(unsigned*)(Vt + dv * 280 + 256 + 2 * k2) = 0u; }
	v_mov_b64_e32 v[2:3], v[100:101]
	v_mov_b64_e32 v[4:5], v[102:103]
	v_cmp_gt_i32_e32 vcc, 0, v17
	v_mov_b64_e32 v[6:7], v[104:105]
	v_mov_b64_e32 v[8:9], v[106:107]
	v_lshlrev_b32_e32 v10, 1, v16
	v_and_b32_e32 v10, 12, v10
	v_readlane_b32 s2, v254, 10
	v_cndmask_b32_e64 v2, v2, 0, vcc
	v_cndmask_b32_e64 v3, v3, 0, vcc
	v_cndmask_b32_e64 v0, v9, 0, vcc
	v_ashrrev_i32_e32 v9, 6, v15
	v_bitop3_b32 v9, v9, v50, 15 bitop3:0x78
	v_cndmask_b32_e64 v6, v6, 0, vcc
	v_lshl_add_u32 v9, v9, 4, 0
	v_cndmask_b32_e64 v7, v7, 0, vcc
	v_perm_b32 v11, v2, v6, s13
	v_add3_u32 v9, v9, v10, v13
	v_perm_b32 v2, v2, v6, s14
	v_cndmask_b32_e64 v8, v8, 0, vcc
	v_cndmask_b32_e64 v4, v4, 0, vcc
	ds_write2_b32 v9, v11, v2 offset1:140
	v_perm_b32 v2, v3, v7, s13
	v_perm_b32 v3, v3, v7, s14
	v_add_u32_e32 v6, 0x400, v9
	v_cndmask_b32_e64 v5, v5, 0, vcc
	ds_write2_b32 v6, v2, v3 offset0:24 offset1:164
	v_perm_b32 v2, v4, v8, s13
	v_perm_b32 v3, v4, v8, s14
	v_add_u32_e32 v4, 0x800, v9
	ds_write2_b32 v4, v2, v3 offset0:48 offset1:188
	v_perm_b32 v2, v5, v0, s13
	v_perm_b32 v0, v5, v0, s14
	v_add_u32_e32 v3, 0xc00, v9
	v_ashrrev_i32_e32 v7, 4, v50
	ds_write2_b32 v3, v2, v0 offset0:72 offset1:212
	v_add_u32_e32 v2, s12, v7
	v_lshlrev_b32_e32 v0, 3, v50
	v_max_i32_e32 v2, 0, v2
	v_mov_b32_e32 v3, v1
	v_and_b32_e32 v0, 0x78, v0
	v_lshlrev_b64 v[2:3], s22, v[2:3]
	v_lshlrev_b32_e32 v0, 1, v0
	v_lshl_add_u64 v[2:3], v[2:3], 0, s[18:19]
	v_mov_b64_e32 v[8:9], s[52:53]
	v_add_u32_e32 v6, s2, v0
	v_mad_u64_u32 v[4:5], s[2:3], v2, s89, v[8:9]
	v_mad_u32_u24 v5, v3, s89, v5
	v_lshl_add_u64 v[2:3], v[4:5], 0, v[0:1]
	s_waitcnt vmcnt(7)
	v_mov_b64_e32 v[2:3], v[108:109]
	v_mov_b64_e32 v[4:5], v[110:111]
	s_movk_i32 s13, 0x110
	v_mad_u64_u32 v[10:11], s[2:3], v7, s13, v[6:7]
	v_ashrrev_i32_e32 v7, 4, v51
	ds_write_b128 v10, v[2:5]
	v_add_u32_e32 v2, s12, v7
	v_max_i32_e32 v2, 0, v2
	v_mov_b32_e32 v3, v1
	v_lshlrev_b64 v[2:3], s22, v[2:3]
	v_lshl_add_u64 v[2:3], v[2:3], 0, s[18:19]
	v_mad_u64_u32 v[4:5], s[2:3], v2, s89, v[8:9]
	v_mad_u32_u24 v5, v3, s89, v5
	v_lshl_add_u64 v[2:3], v[4:5], 0, v[0:1]
	s_waitcnt vmcnt(6)
	v_mov_b64_e32 v[2:3], v[112:113]
	v_mov_b64_e32 v[4:5], v[114:115]
	v_mad_u64_u32 v[10:11], s[2:3], v7, s13, v[6:7]
	v_ashrrev_i32_e32 v7, 4, v14
	ds_write_b128 v10, v[2:5]
	v_add_u32_e32 v2, s12, v7
	v_max_i32_e32 v2, 0, v2
	v_mov_b32_e32 v3, v1
	v_lshlrev_b64 v[2:3], s22, v[2:3]
	v_lshl_add_u64 v[2:3], v[2:3], 0, s[18:19]
	v_mad_u64_u32 v[4:5], s[2:3], v2, s89, v[8:9]
	v_mad_u32_u24 v5, v3, s89, v5
	v_lshl_add_u64 v[2:3], v[4:5], 0, v[0:1]
	s_waitcnt vmcnt(5)
	v_mov_b64_e32 v[2:3], v[116:117]
	v_mov_b64_e32 v[4:5], v[118:119]
	v_mad_u64_u32 v[10:11], s[2:3], v7, s13, v[6:7]
	v_ashrrev_i32_e32 v7, 4, v15
	ds_write_b128 v10, v[2:5]
	v_add_u32_e32 v2, s12, v7
	v_max_i32_e32 v2, 0, v2
	v_mov_b32_e32 v3, v1
	v_lshlrev_b64 v[2:3], s22, v[2:3]
	v_lshl_add_u64 v[2:3], v[2:3], 0, s[18:19]
	v_mad_u64_u32 v[4:5], s[2:3], v2, s89, v[8:9]
	v_mad_u32_u24 v5, v3, s89, v5
	v_lshl_add_u64 v[2:3], v[4:5], 0, v[0:1]
	s_waitcnt vmcnt(4)
	v_mov_b64_e32 v[2:3], v[120:121]
	v_mov_b64_e32 v[4:5], v[122:123]
	v_mad_u64_u32 v[10:11], s[2:3], v7, s13, v[6:7]
	ds_write_b128 v10, v[2:5]
	v_add_u32_e32 v2, 0x800, v50
	v_ashrrev_i32_e32 v7, 4, v2
	v_add_u32_e32 v2, s12, v7
	v_max_i32_e32 v2, 0, v2
	v_mov_b32_e32 v3, v1
	v_lshlrev_b64 v[2:3], s22, v[2:3]
	v_lshl_add_u64 v[2:3], v[2:3], 0, s[18:19]
	v_mad_u64_u32 v[4:5], s[2:3], v2, s89, v[8:9]
	v_mad_u32_u24 v5, v3, s89, v5
	v_lshl_add_u64 v[2:3], v[4:5], 0, v[0:1]
	s_waitcnt vmcnt(3)
	v_mov_b64_e32 v[2:3], v[124:125]
	v_mov_b64_e32 v[4:5], v[126:127]
	v_mad_u64_u32 v[10:11], s[2:3], v7, s13, v[6:7]
	ds_write_b128 v10, v[2:5]
	v_add_u32_e32 v2, 0xa00, v50
	v_ashrrev_i32_e32 v7, 4, v2
	v_add_u32_e32 v2, s12, v7
	v_max_i32_e32 v2, 0, v2
	v_mov_b32_e32 v3, v1
	v_lshlrev_b64 v[2:3], s22, v[2:3]
	v_lshl_add_u64 v[2:3], v[2:3], 0, s[18:19]
	v_mad_u64_u32 v[4:5], s[2:3], v2, s89, v[8:9]
	v_mad_u32_u24 v5, v3, s89, v5
	v_lshl_add_u64 v[2:3], v[4:5], 0, v[0:1]
	s_waitcnt vmcnt(2)
	v_mov_b64_e32 v[2:3], v[128:129]
	v_mov_b64_e32 v[4:5], v[130:131]
	v_mad_u64_u32 v[10:11], s[2:3], v7, s13, v[6:7]
	ds_write_b128 v10, v[2:5]
	v_add_u32_e32 v2, 0xc00, v50
	v_ashrrev_i32_e32 v7, 4, v2
	v_add_u32_e32 v2, s12, v7
	v_max_i32_e32 v2, 0, v2
	v_mov_b32_e32 v3, v1
	v_lshlrev_b64 v[2:3], s22, v[2:3]
	v_lshl_add_u64 v[2:3], v[2:3], 0, s[18:19]
	v_mad_u64_u32 v[4:5], s[2:3], v2, s89, v[8:9]
	v_mad_u32_u24 v5, v3, s89, v5
	v_lshl_add_u64 v[2:3], v[4:5], 0, v[0:1]
	s_waitcnt vmcnt(1)
	v_mov_b64_e32 v[2:3], v[132:133]
	v_mov_b64_e32 v[4:5], v[134:135]
	v_mad_u64_u32 v[10:11], s[2:3], v7, s13, v[6:7]
	v_writelane_b32 v254, s18, 13
	ds_write_b128 v10, v[2:5]
	v_add_u32_e32 v2, 0xe00, v50
	v_ashrrev_i32_e32 v7, 4, v2
	v_add_u32_e32 v2, s12, v7
	v_max_i32_e32 v2, 0, v2
	v_mov_b32_e32 v3, v1
	v_lshlrev_b64 v[2:3], s22, v[2:3]
	v_lshl_add_u64 v[2:3], v[2:3], 0, s[18:19]
	v_mad_u64_u32 v[4:5], s[2:3], v2, s89, v[8:9]
	v_mad_u32_u24 v5, v3, s89, v5
	v_lshl_add_u64 v[2:3], v[4:5], 0, v[0:1]
	s_waitcnt vmcnt(0)
	v_mov_b64_e32 v[2:3], v[136:137]
	v_mov_b64_e32 v[4:5], v[138:139]
	v_mad_u64_u32 v[6:7], s[2:3], v7, s13, v[6:7]
	s_movk_i32 s2, 0x600
	v_writelane_b32 v254, s19, 14
	v_cmp_gt_i32_e32 vcc, s2, v50
	ds_write_b128 v6, v[2:5]
	s_and_saveexec_b64 s[12:13], vcc
	s_cbranch_execz .LBB0_111
	v_max_i32_e32 v2, 0x400, v50
	v_sub_u32_e32 v2, v2, v50
	v_add_u32_e32 v3, 0x1ff, v2
	v_cmp_lt_u32_e32 vcc, s24, v3
	s_mov_b64 s[18:19], -1
	v_mov_b32_e32 v2, v50
	s_and_saveexec_b64 s[14:15], vcc
	s_cbranch_execz .LBB0_108
	v_lshrrev_b32_e32 v2, 9, v3
	v_add_u32_e32 v4, 1, v2
	v_and_b32_e32 v5, 0xfffffe, v4
	s_mov_b64 s[18:19], 0
	v_mov_b32_e32 v6, v5
	v_mov_b64_e32 v[2:3], v[50:51]
	s_mov_b32 s2, 0x2aaaaaab
	s_movk_i32 s3, 0x230

; __device__ void swa_item(const Params& p, int item) {
;     ...
;   bf16x8 qf[4];
;   { long qrow = rowb + (long)(qb * 128 + w * 16 + c) * dil + r;
;     _Pragma("unroll") for (int kk = 0; kk < 4; ++kk) qf[kk] = *(const bf16x8*)(buf + qrow * 4608 + qcol + kk * 32 + q * 8); }
;   __syncthreads();
;   f32x4 S[9];
;   _Pragma("unroll") for (int ci = 0; ci < 9; ++ci) {
;     const int ct = w + ci;
;     f32x4 a = (f32x4){0.f, 0.f, 0.f, 0.f};
;     _Pragma("unroll") for (int kk = 0; kk < 4; ++kk) {
;       bf16x8 kf = *(const bf16x8*)(Ks + (ct * 16 + c) * 136 + kk * 32 + q * 8);
;       a = __builtin_amdgcn_mfma_f32_16x16x32_bf16(qf[kk], kf, a, 0, 0, 0);
;     }
;     S[ci] = a;
;   }
.LBB0_111:
	s_or_b64 exec, exec, s[12:13]
	s_movk_i32 s2, 0x1500
	v_lshlrev_b32_e32 v58, 4, v12
	v_mul_lo_u32 v2, v12, s2
	v_readlane_b32 s12, v254, 10
	v_add_u32_e32 v51, s35, v58
	v_readlane_b32 s26, v254, 13
	v_add_u32_e32 v57, s12, v2
	v_or_b32_e32 v2, v51, v55
	v_ashrrev_i32_e32 v3, 31, v2
	v_lshlrev_b64 v[2:3], s22, v[2:3]
	v_readlane_b32 s27, v254, 14
	v_mov_b64_e32 v[4:5], s[16:17]
	v_and_b32_e32 v52, 48, v50
	v_lshl_add_u64 v[2:3], v[2:3], 0, s[26:27]
	v_mad_u64_u32 v[4:5], s[2:3], v2, s89, v[4:5]
	v_mad_i32_i24 v5, v3, s89, v5
	v_lshl_add_u64 v[2:3], s[0:1], 1, v[4:5]
	v_mov_b32_e32 v53, v1
	v_lshl_add_u64 v[2:3], v[2:3], 0, v[52:53]
	global_load_dwordx4 v[46:49], v[2:3], off
	global_load_dwordx4 v[42:45], v[2:3], off offset:64
	global_load_dwordx4 v[38:41], v[2:3], off offset:128
	global_load_dwordx4 v[34:37], v[2:3], off offset:192
	v_add_u32_e32 v54, s12, v52
	v_or_b32_e32 v53, v58, v55
	s_movk_i32 s3, 0x110
	v_mad_u64_u32 v[30:31], s[0:1], v53, s3, v[54:55]
	s_waitcnt lgkmcnt(0)
	s_barrier
	ds_read_b128 v[2:5], v30
	ds_read_b128 v[6:9], v30 offset:64
	v_bfe_u32 v56, v50, 4, 2
	s_cmp_lg_u32 s34, 0
	s_movk_i32 s2, 0x7f
	v_add_u32_e32 v62, 32, v53
	s_cselect_b64 s[14:15], -1, 0
	s_movk_i32 s18, 0x81
	v_add_u32_e32 v63, 48, v53
	v_add_u32_e32 v61, 16, v53
	v_add_u32_e32 v64, 64, v53
	v_add_u32_e32 v65, 0x50, v53
	v_add_u32_e32 v74, 0x60, v53
	v_add_u32_e32 v75, 0x70, v53
	v_and_b32_e32 v60, 63, v50
	s_waitcnt vmcnt(3) lgkmcnt(1)
	v_mfma_f32_16x16x32_bf16 v[2:5], v[46:49], v[2:5], 0
	ds_read_b128 v[10:13], v30 offset:4416
	ds_read_b128 v[14:17], v30 offset:8768
	ds_read_b128 v[18:21], v30 offset:13120
	s_waitcnt vmcnt(2) lgkmcnt(3)
	v_mfma_f32_16x16x32_bf16 v[2:5], v[42:45], v[6:9], v[2:5]
	ds_read_b128 v[6:9], v30 offset:128
	ds_read_b128 v[22:25], v30 offset:17472
	ds_read_b128 v[26:29], v30 offset:21824
	s_waitcnt vmcnt(1) lgkmcnt(2)
	v_mfma_f32_16x16x32_bf16 v[2:5], v[38:41], v[6:9], v[2:5]
	ds_read_b128 v[6:9], v30 offset:192
	ds_read_b128 v[66:69], v30 offset:26176
	ds_read_b128 v[70:73], v30 offset:30528
	s_waitcnt vmcnt(0) lgkmcnt(2)
	v_mfma_f32_16x16x32_bf16 v[2:5], v[34:37], v[6:9], v[2:5]
	ds_read_b128 v[6:9], v30 offset:4352
	s_waitcnt lgkmcnt(0)
	v_mfma_f32_16x16x32_bf16 v[6:9], v[46:49], v[6:9], 0
	v_mfma_f32_16x16x32_bf16 v[6:9], v[42:45], v[10:13], v[6:9]
	ds_read_b128 v[10:13], v30 offset:4480
	s_waitcnt lgkmcnt(0)
	v_mfma_f32_16x16x32_bf16 v[6:9], v[38:41], v[10:13], v[6:9]
	ds_read_b128 v[10:13], v30 offset:4544
	s_waitcnt lgkmcnt(0)
	v_mfma_f32_16x16x32_bf16 v[6:9], v[34:37], v[10:13], v[6:9]
	ds_read_b128 v[10:13], v30 offset:8704
	s_waitcnt lgkmcnt(0)
	v_mfma_f32_16x16x32_bf16 v[10:13], v[46:49], v[10:13], 0
	v_mfma_f32_16x16x32_bf16 v[10:13], v[42:45], v[14:17], v[10:13]
	ds_read_b128 v[14:17], v30 offset:8832
	s_waitcnt lgkmcnt(0)
	v_mfma_f32_16x16x32_bf16 v[10:13], v[38:41], v[14:17], v[10:13]
	ds_read_b128 v[14:17], v30 offset:8896
	s_waitcnt lgkmcnt(0)
	v_mfma_f32_16x16x32_bf16 v[10:13], v[34:37], v[14:17], v[10:13]
	ds_read_b128 v[14:17], v30 offset:13056
	s_waitcnt lgkmcnt(0)
	v_mfma_f32_16x16x32_bf16 v[14:17], v[46:49], v[14:17], 0
	v_mfma_f32_16x16x32_bf16 v[14:17], v[42:45], v[18:21], v[14:17]
	ds_read_b128 v[18:21], v30 offset:13184
	s_waitcnt lgkmcnt(0)
	v_mfma_f32_16x16x32_bf16 v[14:17], v[38:41], v[18:21], v[14:17]
	ds_read_b128 v[18:21], v30 offset:13248
	s_waitcnt lgkmcnt(0)
	v_mfma_f32_16x16x32_bf16 v[14:17], v[34:37], v[18:21], v[14:17]
	ds_read_b128 v[18:21], v30 offset:17408
	s_waitcnt lgkmcnt(0)
	v_mfma_f32_16x16x32_bf16 v[18:21], v[46:49], v[18:21], 0
	v_mfma_f32_16x16x32_bf16 v[18:21], v[42:45], v[22:25], v[18:21]
	ds_read_b128 v[22:25], v30 offset:17536
	s_waitcnt lgkmcnt(0)
	v_mfma_f32_16x16x32_bf16 v[18:21], v[38:41], v[22:25], v[18:21]
	ds_read_b128 v[22:25], v30 offset:17600
	s_waitcnt lgkmcnt(0)
	v_mfma_f32_16x16x32_bf16 v[18:21], v[34:37], v[22:25], v[18:21]
	ds_read_b128 v[22:25], v30 offset:21760
	s_waitcnt lgkmcnt(0)
	v_mfma_f32_16x16x32_bf16 v[22:25], v[46:49], v[22:25], 0
	v_mfma_f32_16x16x32_bf16 v[22:25], v[42:45], v[26:29], v[22:25]
	ds_read_b128 v[26:29], v30 offset:21888
	s_waitcnt lgkmcnt(0)
	v_mfma_f32_16x16x32_bf16 v[22:25], v[38:41], v[26:29], v[22:25]
	ds_read_b128 v[26:29], v30 offset:21952
	s_waitcnt lgkmcnt(0)
	v_mfma_f32_16x16x32_bf16 v[22:25], v[34:37], v[26:29], v[22:25]
	ds_read_b128 v[26:29], v30 offset:26112
	s_waitcnt lgkmcnt(0)
	v_mfma_f32_16x16x32_bf16 v[26:29], v[46:49], v[26:29], 0
	v_mfma_f32_16x16x32_bf16 v[26:29], v[42:45], v[66:69], v[26:29]
	ds_read_b128 v[66:69], v30 offset:26240
	s_waitcnt lgkmcnt(0)
	v_mfma_f32_16x16x32_bf16 v[26:29], v[38:41], v[66:69], v[26:29]
	ds_read_b128 v[66:69], v30 offset:26304
	s_waitcnt lgkmcnt(0)
	v_mfma_f32_16x16x32_bf16 v[26:29], v[34:37], v[66:69], v[26:29]
	ds_read_b128 v[66:69], v30 offset:30464
	s_waitcnt lgkmcnt(0)
	v_mfma_f32_16x16x32_bf16 v[66:69], v[46:49], v[66:69], 0
	v_mfma_f32_16x16x32_bf16 v[66:69], v[42:45], v[70:73], v[66:69]
	ds_read_b128 v[70:73], v30 offset:30592
	ds_read_b128 v[30:33], v30 offset:30656
	s_waitcnt lgkmcnt(1)
	v_mfma_f32_16x16x32_bf16 v[66:69], v[38:41], v[70:73], v[66:69]
	v_add_u32_e32 v72, 0x80, v58
	v_or_b32_e32 v59, v72, v55
	v_mad_u64_u32 v[70:71], s[0:1], v59, s3, v[54:55]
	s_waitcnt lgkmcnt(0)
	v_mfma_f32_16x16x32_bf16 v[30:33], v[34:37], v[30:33], v[66:69]
	v_cmp_lt_i32_e64 s[0:1], s2, v53
	s_or_b64 s[12:13], s[14:15], s[0:1]
	v_cmp_lt_i32_e64 s[0:1], s2, v62
	ds_read_b128 v[66:69], v70
	s_waitcnt lgkmcnt(0)
	v_mfma_f32_16x16x32_bf16 v[46:49], v[46:49], v[66:69], 0
	ds_read_b128 v[66:69], v70 offset:64
	s_or_b64 s[38:39], s[14:15], s[0:1]
	v_cmp_lt_i32_e64 s[0:1], s2, v63
	s_waitcnt lgkmcnt(0)
; __device__ __forceinline__ float fexp(float x) { return __builtin_amdgcn_exp2f(x * 1.4426950408889634f); }
; #define SHX(v, m) shx_((v), (m), lane)
; __device__ void swa_item(const Params& p, int item) {
;     ...
;   float mx[4], ls[4];
;   _Pragma("unroll") for (int jj = 0; jj < 4; ++jj) {
;     const int qi = w * 16 + q * 4 + jj;
;     float m = -1e30f;
;     _Pragma("unroll") for (int ci = 0; ci < 9; ++ci) {
;       int kj = (w + ci) * 16 + c; int dist = qi + 128 - kj;
;       bool valid = (dist >= 0) && (dist <= 128) && (qb > 0 || kj >= 128);
;       float s = valid ? S[ci][jj] : -1e30f;
;       S[ci][jj] = s; m = fmaxf(m, s);
;     }
;     m = fmaxf(m, SHX(m, 1)); m = fmaxf(m, SHX(m, 2)); m = fmaxf(m, SHX(m, 4)); m = fmaxf(m, SHX(m, 8));
;     float l = 0.f;
;     _Pragma("unroll") for (int ci = 0; ci < 9; ++ci) {
;       float s = S[ci][jj];
;       float pv = (s > -1e29f) ? fexp(s - m) : 0.f;
;       S[ci][jj] = pv; l += pv;
;     }
;     l += SHX(l, 1); l += SHX(l, 2); l += SHX(l, 4); l += SHX(l, 8);
;     mx[jj] = m; ls[jj] = l;
;   }
;   __syncthreads();
	v_mfma_f32_16x16x32_bf16 v[42:45], v[42:45], v[66:69], v[46:49]
	v_mov_b32_e32 v66, 0xf149f2ca
	s_nop 1
	ds_read_b128 v[46:49], v70 offset:128
	s_or_b64 s[40:41], s[14:15], s[0:1]
	s_waitcnt lgkmcnt(0)
	v_mfma_f32_16x16x32_bf16 v[38:41], v[38:41], v[46:49], v[42:45]
	s_nop 2
	ds_read_b128 v[42:45], v70 offset:192
	v_cmp_lt_i32_e64 s[0:1], s2, v64
	s_or_b64 s[42:43], s[14:15], s[0:1]
	s_waitcnt lgkmcnt(0)
	v_mfma_f32_16x16x32_bf16 v[34:37], v[34:37], v[42:45], v[38:41]
	v_cmp_lt_i32_e64 s[0:1], s2, v65
	s_nop 1
	v_lshlrev_b32_e32 v38, 2, v56
	v_or_b32_e32 v43, v72, v38
	v_sub_u32_e32 v44, v43, v53
	v_cmp_gt_u32_e32 vcc, s18, v44
	s_and_b64 vcc, vcc, s[12:13]
	v_cndmask_b32_e64 v45, v66, v10, s[38:39]
	v_cndmask_b32_e32 v2, v66, v2, vcc
	v_cmp_lt_i32_e32 vcc, s2, v61
	v_max_f32_e32 v44, v2, v2
	s_or_b64 vcc, s[14:15], vcc
	v_max_f32_e32 v44, 0xf149f2ca, v44
	v_cndmask_b32_e32 v6, v66, v6, vcc
	s_or_b64 s[44:45], s[14:15], s[0:1]
	v_cmp_lt_i32_e64 s[0:1], s2, v74
	v_max3_f32 v10, v44, v6, v45
	v_cndmask_b32_e64 v44, v66, v18, s[42:43]
	s_or_b64 s[46:47], s[14:15], s[0:1]
	v_cmp_lt_i32_e64 s[0:1], s2, v75
	v_sub_u32_e32 v18, v38, v55
	v_cmp_lt_i32_e64 s[50:51], s2, v59
	v_cndmask_b32_e64 v14, v66, v14, s[40:41]
	s_or_b64 s[48:49], s[14:15], s[0:1]
	v_cmp_gt_u32_e64 s[0:1], s18, v18
	s_or_b64 s[14:15], s[14:15], s[50:51]
	v_max3_f32 v10, v10, v14, v44
	v_cndmask_b32_e64 v46, v66, v22, s[44:45]
	v_cndmask_b32_e64 v26, v66, v26, s[46:47]
	s_and_b64 s[0:1], s[0:1], s[14:15]
	v_lshlrev_b32_e32 v39, 2, v60
	v_max3_f32 v10, v10, v46, v26
	v_cndmask_b32_e64 v47, v66, v30, s[48:49]
	v_cndmask_b32_e64 v48, v66, v34, s[0:1]
	v_xor_b32_e32 v42, 4, v39
	v_max3_f32 v10, v10, v47, v48
	ds_bpermute_b32 v18, v42, v10
	v_xor_b32_e32 v41, 8, v39
	v_xor_b32_e32 v40, 16, v39
	v_xor_b32_e32 v39, 32, v39
	s_mov_b32 s2, 0xefa18f08
	s_waitcnt lgkmcnt(0)
	v_max_f32_e32 v18, v18, v18
	v_max_f32_e32 v10, v10, v18
	ds_bpermute_b32 v18, v41, v10
	v_cmp_lt_f32_e64 s[0:1], s2, v2
	v_cndmask_b32_e32 v7, v66, v7, vcc
	v_cndmask_b32_e64 v15, v66, v15, s[40:41]
	v_cndmask_b32_e64 v49, v66, v23, s[44:45]
	s_waitcnt lgkmcnt(0)
	v_max_f32_e32 v18, v18, v18
	v_max_f32_e32 v10, v10, v18
	ds_bpermute_b32 v18, v40, v10
	v_cndmask_b32_e64 v27, v66, v27, s[46:47]
	v_cndmask_b32_e64 v54, v66, v31, s[48:49]
	v_cndmask_b32_e32 v8, v66, v8, vcc
	v_cndmask_b32_e64 v12, v66, v12, s[38:39]
	s_waitcnt lgkmcnt(0)
	v_max_f32_e32 v18, v18, v18
	v_max_f32_e32 v10, v10, v18
	ds_bpermute_b32 v18, v39, v10
	v_cndmask_b32_e64 v60, v66, v32, s[48:49]
	v_cndmask_b32_e64 v16, v66, v16, s[40:41]
	v_cndmask_b32_e64 v20, v66, v20, s[42:43]
	v_cndmask_b32_e64 v28, v66, v28, s[46:47]
	s_waitcnt lgkmcnt(0)
	v_max_f32_e32 v18, v18, v18
	v_max_f32_e32 v22, v10, v18
	v_sub_f32_e32 v2, v2, v22
	v_mul_f32_e32 v2, 0x3fb8aa3b, v2
	v_exp_f32_e32 v2, v2
	v_sub_f32_e32 v34, v46, v22
	v_mul_f32_e32 v34, 0x3fb8aa3b, v34
	v_exp_f32_e32 v34, v34
	v_cndmask_b32_e64 v2, 0, v2, s[0:1]
	v_cmp_lt_f32_e64 s[0:1], s2, v6
	v_sub_f32_e32 v6, v6, v22
	v_mul_f32_e32 v6, 0x3fb8aa3b, v6
	v_exp_f32_e32 v6, v6
	v_add_f32_e32 v18, 0, v2
	v_cndmask_b32_e32 v9, v66, v9, vcc
	v_cndmask_b32_e64 v13, v66, v13, s[38:39]
	v_cndmask_b32_e64 v10, 0, v6, s[0:1]
	v_sub_f32_e32 v6, v45, v22
	v_mul_f32_e32 v6, 0x3fb8aa3b, v6
	v_exp_f32_e32 v6, v6
	v_cmp_lt_f32_e64 s[0:1], s2, v45
	v_add_f32_e32 v18, v10, v18
	v_cndmask_b32_e64 v17, v66, v17, s[40:41]
	v_cndmask_b32_e64 v6, 0, v6, s[0:1]
	v_cmp_lt_f32_e64 s[0:1], s2, v14
	v_sub_f32_e32 v14, v14, v22
	v_mul_f32_e32 v14, 0x3fb8aa3b, v14
	v_exp_f32_e32 v14, v14
	v_add_f32_e32 v30, v6, v18
	v_cndmask_b32_e64 v21, v66, v21, s[42:43]
	v_cndmask_b32_e64 v29, v66, v29, s[46:47]
	v_cndmask_b32_e64 v18, 0, v14, s[0:1]
	v_sub_f32_e32 v14, v44, v22
	v_mul_f32_e32 v14, 0x3fb8aa3b, v14
	v_exp_f32_e32 v14, v14
	v_cmp_lt_f32_e64 s[0:1], s2, v44
	v_add_f32_e32 v30, v18, v30
	v_cndmask_b32_e64 v33, v66, v33, s[48:49]
	v_cndmask_b32_e64 v14, 0, v14, s[0:1]
	v_cmp_lt_f32_e64 s[0:1], s2, v46
	v_add_f32_e32 v30, v14, v30
	s_nop 0
	v_cndmask_b32_e64 v34, 0, v34, s[0:1]
	v_cmp_lt_f32_e64 s[0:1], s2, v26
	v_sub_f32_e32 v26, v26, v22
	v_mul_f32_e32 v26, 0x3fb8aa3b, v26
	v_exp_f32_e32 v26, v26
	v_add_f32_e32 v44, v34, v30
	s_barrier
	global_load_dword v243, v240, s[52:53]
	global_load_dword v243, v241, s[52:53]
	global_load_dword v243, v242, s[52:53]
	v_cndmask_b32_e64 v30, 0, v26, s[0:1]
	v_add_f32_e32 v26, v30, v44
	v_sub_f32_e32 v44, v47, v22
	v_mul_f32_e32 v44, 0x3fb8aa3b, v44
	v_exp_f32_e32 v44, v44
	v_cmp_lt_f32_e64 s[0:1], s2, v47
	s_nop 1
	v_cndmask_b32_e64 v45, 0, v44, s[0:1]
	v_sub_f32_e32 v44, v48, v22
	v_mul_f32_e32 v44, 0x3fb8aa3b, v44
	v_exp_f32_e32 v44, v44
	v_cmp_lt_f32_e64 s[0:1], s2, v48
	v_add_f32_e32 v26, v45, v26
	v_cndmask_b32_e64 v48, v66, v11, s[38:39]
	v_cndmask_b32_e64 v44, 0, v44, s[0:1]
	v_add_f32_e32 v26, v44, v26
	ds_bpermute_b32 v46, v42, v26
	s_waitcnt lgkmcnt(0)
	v_add_f32_e32 v26, v26, v46
	ds_bpermute_b32 v46, v41, v26
	s_waitcnt lgkmcnt(0)
	v_add_f32_e32 v26, v26, v46
	ds_bpermute_b32 v46, v40, v26
	s_waitcnt lgkmcnt(0)
	v_add_f32_e32 v26, v26, v46
	ds_bpermute_b32 v46, v39, v26
	s_waitcnt lgkmcnt(0)
	v_add_f32_e32 v26, v26, v46
	v_or_b32_e32 v46, 1, v43
	v_sub_u32_e32 v47, v46, v53
	v_cmp_gt_u32_e64 s[0:1], s18, v47
	s_and_b64 s[0:1], s[0:1], s[12:13]
	s_nop 0
	v_cndmask_b32_e64 v3, v66, v3, s[0:1]
	v_max_f32_e32 v47, v3, v3
	v_max_f32_e32 v47, 0xf149f2ca, v47
	v_max3_f32 v11, v47, v7, v48
	v_cndmask_b32_e64 v47, v66, v19, s[42:43]
	v_sub_u32_e32 v19, v46, v59
	v_cmp_gt_u32_e64 s[0:1], s18, v19
	v_max3_f32 v11, v11, v15, v47
	s_and_b64 s[0:1], s[0:1], s[14:15]
	v_max3_f32 v11, v11, v49, v27
	v_cndmask_b32_e64 v35, v66, v35, s[0:1]
	v_max3_f32 v11, v11, v54, v35
	ds_bpermute_b32 v19, v42, v11
	v_cmp_lt_f32_e64 s[0:1], s2, v3
	s_waitcnt lgkmcnt(0)
; __device__ __forceinline__ float fexp(float x) { return __builtin_amdgcn_exp2f(x * 1.4426950408889634f); }
; #define SHX(v, m) shx_((v), (m), lane)
; __device__ void swa_item(const Params& p, int item) {
;     ...
;   _Pragma("unroll") for (int jj = 0; jj < 4; ++jj) {
;     const int qi = w * 16 + q * 4 + jj;
;     float m = -1e30f;
;     _Pragma("unroll") for (int ci = 0; ci < 9; ++ci) {
;       int kj = (w + ci) * 16 + c; int dist = qi + 128 - kj;
;       bool valid = (dist >= 0) && (dist <= 128) && (qb > 0 || kj >= 128);
;       float s = valid ? S[ci][jj] : -1e30f;
;       S[ci][jj] = s; m = fmaxf(m, s);
;     }
;     m = fmaxf(m, SHX(m, 1)); m = fmaxf(m, SHX(m, 2)); m = fmaxf(m, SHX(m, 4)); m = fmaxf(m, SHX(m, 8));
;     float l = 0.f;
;     _Pragma("unroll") for (int ci = 0; ci < 9; ++ci) {
;       float s = S[ci][jj];
;       float pv = (s > -1e29f) ? fexp(s - m) : 0.f;
;       S[ci][jj] = pv; l += pv;
;     }
;     l += SHX(l, 1); l += SHX(l, 2); l += SHX(l, 4); l += SHX(l, 8);
;     mx[jj] = m; ls[jj] = l;
;   }
	v_max_f32_e32 v19, v19, v19
	v_max_f32_e32 v11, v11, v19
	ds_bpermute_b32 v19, v41, v11
	s_waitcnt lgkmcnt(0)
	v_max_f32_e32 v19, v19, v19
	v_max_f32_e32 v11, v11, v19
	ds_bpermute_b32 v19, v40, v11
	s_waitcnt lgkmcnt(0)
	v_max_f32_e32 v19, v19, v19
	v_max_f32_e32 v11, v11, v19
	ds_bpermute_b32 v19, v39, v11
	s_waitcnt lgkmcnt(0)
	v_max_f32_e32 v19, v19, v19
	v_max_f32_e32 v23, v11, v19
	v_sub_f32_e32 v3, v3, v23
	v_mul_f32_e32 v3, 0x3fb8aa3b, v3
	v_exp_f32_e32 v3, v3
	v_sub_f32_e32 v46, v49, v23
	v_mul_f32_e32 v46, 0x3fb8aa3b, v46
	v_exp_f32_e32 v46, v46
	v_cndmask_b32_e64 v3, 0, v3, s[0:1]
	v_cmp_lt_f32_e64 s[0:1], s2, v7
	v_sub_f32_e32 v7, v7, v23
	v_mul_f32_e32 v7, 0x3fb8aa3b, v7
	v_exp_f32_e32 v7, v7
	v_add_f32_e32 v19, 0, v3
	v_cndmask_b32_e64 v11, 0, v7, s[0:1]
	v_sub_f32_e32 v7, v48, v23
	v_mul_f32_e32 v7, 0x3fb8aa3b, v7
	v_exp_f32_e32 v7, v7
	v_cmp_lt_f32_e64 s[0:1], s2, v48
	v_add_f32_e32 v19, v11, v19
	s_nop 0
	v_cndmask_b32_e64 v7, 0, v7, s[0:1]
	v_cmp_lt_f32_e64 s[0:1], s2, v15
	v_sub_f32_e32 v15, v15, v23
	v_mul_f32_e32 v15, 0x3fb8aa3b, v15
	v_exp_f32_e32 v15, v15
	v_add_f32_e32 v31, v7, v19
	v_cndmask_b32_e64 v19, 0, v15, s[0:1]
	v_sub_f32_e32 v15, v47, v23
	v_mul_f32_e32 v15, 0x3fb8aa3b, v15
	v_exp_f32_e32 v15, v15
	v_cmp_lt_f32_e64 s[0:1], s2, v47
	v_add_f32_e32 v31, v19, v31
	s_nop 0
	v_cndmask_b32_e64 v15, 0, v15, s[0:1]
	v_cmp_lt_f32_e64 s[0:1], s2, v49
	v_add_f32_e32 v31, v15, v31
	s_nop 0
	v_cndmask_b32_e64 v46, 0, v46, s[0:1]
	v_cmp_lt_f32_e64 s[0:1], s2, v27
	v_sub_f32_e32 v27, v27, v23
	v_mul_f32_e32 v27, 0x3fb8aa3b, v27
	v_exp_f32_e32 v27, v27
	v_add_f32_e32 v47, v46, v31
	v_cndmask_b32_e64 v31, 0, v27, s[0:1]
	v_add_f32_e32 v27, v31, v47
	v_sub_f32_e32 v47, v54, v23
	v_mul_f32_e32 v47, 0x3fb8aa3b, v47
	v_exp_f32_e32 v47, v47
	v_cmp_lt_f32_e64 s[0:1], s2, v54
	v_cndmask_b32_e64 v54, v66, v24, s[44:45]
	s_nop 0
	v_cndmask_b32_e64 v47, 0, v47, s[0:1]
	v_cmp_lt_f32_e64 s[0:1], s2, v35
	v_sub_f32_e32 v35, v35, v23
	v_mul_f32_e32 v35, 0x3fb8aa3b, v35
	v_exp_f32_e32 v35, v35
	v_add_f32_e32 v27, v47, v27
	v_cndmask_b32_e64 v35, 0, v35, s[0:1]
	v_add_f32_e32 v27, v35, v27
	ds_bpermute_b32 v48, v42, v27
	s_waitcnt lgkmcnt(0)
	v_add_f32_e32 v27, v27, v48
	ds_bpermute_b32 v48, v41, v27
	s_waitcnt lgkmcnt(0)
	v_add_f32_e32 v27, v27, v48
	ds_bpermute_b32 v48, v40, v27
	s_waitcnt lgkmcnt(0)
	v_add_f32_e32 v27, v27, v48
	ds_bpermute_b32 v48, v39, v27
	s_waitcnt lgkmcnt(0)
	v_add_f32_e32 v27, v27, v48
	v_or_b32_e32 v48, 2, v43
	v_sub_u32_e32 v49, v48, v53
	v_cmp_gt_u32_e64 s[0:1], s18, v49
	s_and_b64 s[0:1], s[0:1], s[12:13]
	v_sub_u32_e32 v32, v48, v59
	v_cndmask_b32_e64 v4, v66, v4, s[0:1]
	v_max_f32_e32 v49, v4, v4
	v_max_f32_e32 v49, 0xf149f2ca, v49
	v_max3_f32 v49, v49, v8, v12
	v_cmp_gt_u32_e64 s[0:1], s18, v32
	v_max3_f32 v49, v49, v16, v20
	s_and_b64 s[0:1], s[0:1], s[14:15]
	v_max3_f32 v24, v49, v54, v28
	v_cndmask_b32_e64 v61, v66, v36, s[0:1]
	v_max3_f32 v24, v24, v60, v61
	ds_bpermute_b32 v32, v42, v24
	v_cmp_lt_f32_e64 s[0:1], s2, v4
	v_or_b32_e32 v43, 3, v43
	v_sub_u32_e32 v53, v43, v53
	v_sub_u32_e32 v43, v43, v59
	s_waitcnt lgkmcnt(0)
	v_max_f32_e32 v32, v32, v32
	v_max_f32_e32 v24, v24, v32
	ds_bpermute_b32 v32, v41, v24
	v_cmp_gt_u32_e32 vcc, s18, v43
	s_and_b64 vcc, vcc, s[14:15]
	s_waitcnt lgkmcnt(0)
	v_max_f32_e32 v32, v32, v32
	v_max_f32_e32 v24, v24, v32
	ds_bpermute_b32 v32, v40, v24
	v_cndmask_b32_e32 v37, v66, v37, vcc
	s_waitcnt lgkmcnt(0)
	v_max_f32_e32 v32, v32, v32
	v_max_f32_e32 v24, v24, v32
	ds_bpermute_b32 v32, v39, v24
	s_waitcnt lgkmcnt(0)
	v_max_f32_e32 v32, v32, v32
	v_max_f32_e32 v24, v24, v32
	v_sub_f32_e32 v4, v4, v24
	v_mul_f32_e32 v4, 0x3fb8aa3b, v4
	v_exp_f32_e32 v4, v4
	s_nop 0
	v_cndmask_b32_e64 v4, 0, v4, s[0:1]
	v_cmp_lt_f32_e64 s[0:1], s2, v8
	v_sub_f32_e32 v8, v8, v24
	v_mul_f32_e32 v8, 0x3fb8aa3b, v8
	v_exp_f32_e32 v8, v8
	v_add_f32_e32 v32, 0, v4
	v_cndmask_b32_e64 v8, 0, v8, s[0:1]
	v_cmp_lt_f32_e64 s[0:1], s2, v12
	v_sub_f32_e32 v12, v12, v24
	v_mul_f32_e32 v12, 0x3fb8aa3b, v12
	v_exp_f32_e32 v12, v12
	v_add_f32_e32 v32, v8, v32
	v_cndmask_b32_e64 v12, 0, v12, s[0:1]
	v_cmp_lt_f32_e64 s[0:1], s2, v16
	v_sub_f32_e32 v16, v16, v24
	v_mul_f32_e32 v16, 0x3fb8aa3b, v16
	v_exp_f32_e32 v16, v16
	v_add_f32_e32 v32, v12, v32
	v_cndmask_b32_e64 v16, 0, v16, s[0:1]
	v_cmp_lt_f32_e64 s[0:1], s2, v20
	v_sub_f32_e32 v20, v20, v24
	v_mul_f32_e32 v20, 0x3fb8aa3b, v20
	v_exp_f32_e32 v20, v20
	v_add_f32_e32 v36, v16, v32
	v_cndmask_b32_e64 v32, 0, v20, s[0:1]
	v_add_f32_e32 v20, v32, v36
	v_sub_f32_e32 v36, v54, v24
	v_mul_f32_e32 v36, 0x3fb8aa3b, v36
	v_exp_f32_e32 v36, v36
	v_cmp_lt_f32_e64 s[0:1], s2, v54
	s_nop 1
	v_cndmask_b32_e64 v49, 0, v36, s[0:1]
	v_cmp_lt_f32_e64 s[0:1], s2, v28
	v_sub_f32_e32 v28, v28, v24
	v_mul_f32_e32 v28, 0x3fb8aa3b, v28
	v_exp_f32_e32 v28, v28
	v_add_f32_e32 v20, v49, v20
	v_cndmask_b32_e64 v48, 0, v28, s[0:1]
	v_sub_f32_e32 v28, v60, v24
	v_mul_f32_e32 v28, 0x3fb8aa3b, v28
	v_exp_f32_e32 v28, v28
	v_cmp_lt_f32_e64 s[0:1], s2, v60
	v_add_f32_e32 v20, v48, v20
	s_nop 0
	v_cndmask_b32_e64 v36, 0, v28, s[0:1]
	v_add_f32_e32 v28, v36, v20
	v_sub_f32_e32 v20, v61, v24
	v_mul_f32_e32 v20, 0x3fb8aa3b, v20
	v_exp_f32_e32 v20, v20
	v_cmp_lt_f32_e64 s[0:1], s2, v61
	s_nop 1
	v_cndmask_b32_e64 v20, 0, v20, s[0:1]
	v_add_f32_e32 v28, v20, v28
	ds_bpermute_b32 v54, v42, v28
	v_cmp_gt_u32_e64 s[0:1], s18, v53
	s_and_b64 s[0:1], s[0:1], s[12:13]
	s_waitcnt lgkmcnt(0)
	v_add_f32_e32 v28, v28, v54
	ds_bpermute_b32 v54, v41, v28
	v_cndmask_b32_e64 v5, v66, v5, s[0:1]
	v_max_f32_e32 v53, v5, v5
	v_max_f32_e32 v53, 0xf149f2ca, v53
	v_max3_f32 v53, v53, v9, v13
	s_waitcnt lgkmcnt(0)
; __device__ __forceinline__ float fexp(float x) { return __builtin_amdgcn_exp2f(x * 1.4426950408889634f); }
; #define SHX(v, m) shx_((v), (m), lane)
; __device__ void swa_item(const Params& p, int item) {
;     ...
;   _Pragma("unroll") for (int jj = 0; jj < 4; ++jj) {
;     const int qi = w * 16 + q * 4 + jj;
;     float m = -1e30f;
;     _Pragma("unroll") for (int ci = 0; ci < 9; ++ci) {
;       int kj = (w + ci) * 16 + c; int dist = qi + 128 - kj;
;       bool valid = (dist >= 0) && (dist <= 128) && (qb > 0 || kj >= 128);
;       float s = valid ? S[ci][jj] : -1e30f;
;       S[ci][jj] = s; m = fmaxf(m, s);
;     }
;     m = fmaxf(m, SHX(m, 1)); m = fmaxf(m, SHX(m, 2)); m = fmaxf(m, SHX(m, 4)); m = fmaxf(m, SHX(m, 8));
;     float l = 0.f;
;     _Pragma("unroll") for (int ci = 0; ci < 9; ++ci) {
;       float s = S[ci][jj];
;       float pv = (s > -1e29f) ? fexp(s - m) : 0.f;
;       S[ci][jj] = pv; l += pv;
;     }
;     l += SHX(l, 1); l += SHX(l, 2); l += SHX(l, 4); l += SHX(l, 8);
;     mx[jj] = m; ls[jj] = l;
;   }
;   __syncthreads();
;   _Pragma("unroll") for (int ci = 0; ci < 9; ++ci) _Pragma("unroll") for (int jj = 0; jj < 4; ++jj) Pl[(q * 4 + jj) * 168 + ci * 16 + c] = f2bf(S[ci][jj]);
;   _Pragma("unroll") for (int jj = 0; jj < 4; ++jj) Pl[(q * 4 + jj) * 168 + 144 + c] = 0;
	v_add_f32_e32 v28, v28, v54
	ds_bpermute_b32 v54, v40, v28
	v_max3_f32 v53, v53, v17, v21
	v_cmp_lt_f32_e32 vcc, s2, v5
	s_movk_i32 s0, 0x540
	s_waitcnt lgkmcnt(0)
	v_add_f32_e32 v28, v28, v54
	ds_bpermute_b32 v54, v39, v28
	s_waitcnt lgkmcnt(0)
	v_add_f32_e32 v28, v28, v54
	v_cndmask_b32_e64 v54, v66, v25, s[44:45]
	v_max3_f32 v25, v53, v54, v29
	v_max3_f32 v25, v25, v33, v37
	ds_bpermute_b32 v43, v42, v25
	s_waitcnt lgkmcnt(0)
	v_max_f32_e32 v43, v43, v43
	v_max_f32_e32 v25, v25, v43
	ds_bpermute_b32 v43, v41, v25
	s_waitcnt lgkmcnt(0)
	v_max_f32_e32 v43, v43, v43
	v_max_f32_e32 v25, v25, v43
	ds_bpermute_b32 v43, v40, v25
	s_waitcnt lgkmcnt(0)
	v_max_f32_e32 v43, v43, v43
	v_max_f32_e32 v25, v25, v43
	ds_bpermute_b32 v43, v39, v25
	s_waitcnt lgkmcnt(0)
	v_max_f32_e32 v43, v43, v43
	v_max_f32_e32 v25, v25, v43
	v_sub_f32_e32 v5, v5, v25
	v_mul_f32_e32 v5, 0x3fb8aa3b, v5
	v_exp_f32_e32 v5, v5
	v_sub_f32_e32 v53, v54, v25
	v_mul_f32_e32 v53, 0x3fb8aa3b, v53
	v_exp_f32_e32 v53, v53
	v_cndmask_b32_e32 v5, 0, v5, vcc
	v_cmp_lt_f32_e32 vcc, s2, v9
	v_sub_f32_e32 v9, v9, v25
	v_mul_f32_e32 v9, 0x3fb8aa3b, v9
	v_exp_f32_e32 v9, v9
	v_add_f32_e32 v43, 0, v5
	v_cndmask_b32_e32 v9, 0, v9, vcc
	v_cmp_lt_f32_e32 vcc, s2, v13
	v_sub_f32_e32 v13, v13, v25
	v_mul_f32_e32 v13, 0x3fb8aa3b, v13
	v_exp_f32_e32 v13, v13
	v_add_f32_e32 v43, v9, v43
	v_cndmask_b32_e32 v13, 0, v13, vcc
	v_cmp_lt_f32_e32 vcc, s2, v17
	v_sub_f32_e32 v17, v17, v25
	v_mul_f32_e32 v17, 0x3fb8aa3b, v17
	v_exp_f32_e32 v17, v17
	v_add_f32_e32 v43, v13, v43
	v_cndmask_b32_e32 v17, 0, v17, vcc
	v_cmp_lt_f32_e32 vcc, s2, v21
	v_sub_f32_e32 v21, v21, v25
	v_mul_f32_e32 v21, 0x3fb8aa3b, v21
	v_exp_f32_e32 v21, v21
	v_add_f32_e32 v43, v17, v43
	v_cndmask_b32_e32 v21, 0, v21, vcc
	v_cmp_lt_f32_e32 vcc, s2, v54
	v_add_f32_e32 v43, v21, v43
	s_nop 0
	v_cndmask_b32_e32 v53, 0, v53, vcc
	v_cmp_lt_f32_e32 vcc, s2, v29
	v_sub_f32_e32 v29, v29, v25
	v_mul_f32_e32 v29, 0x3fb8aa3b, v29
	v_exp_f32_e32 v29, v29
	v_add_f32_e32 v43, v53, v43
	v_cndmask_b32_e32 v54, 0, v29, vcc
	v_cmp_lt_f32_e32 vcc, s2, v33
	v_sub_f32_e32 v33, v33, v25
	v_mul_f32_e32 v33, 0x3fb8aa3b, v33
	v_exp_f32_e32 v33, v33
	v_add_f32_e32 v29, v54, v43
	v_or_b32_e32 v43, 1, v38
	v_cndmask_b32_e32 v33, 0, v33, vcc
	v_cmp_lt_f32_e32 vcc, s2, v37
	v_sub_f32_e32 v37, v37, v25
	v_mul_f32_e32 v37, 0x3fb8aa3b, v37
	v_exp_f32_e32 v37, v37
	v_add_f32_e32 v29, v33, v29
	s_movk_i32 s2, 0xc0
	v_cndmask_b32_e32 v37, 0, v37, vcc
	v_add_f32_e32 v29, v37, v29
	ds_bpermute_b32 v42, v42, v29
	s_waitcnt lgkmcnt(0)
	v_add_f32_e32 v29, v29, v42
	ds_bpermute_b32 v41, v41, v29
	s_waitcnt lgkmcnt(0)
	v_add_f32_e32 v29, v29, v41
	ds_bpermute_b32 v40, v40, v29
	v_bfe_u32 v41, v2, 16, 1
	v_add3_u32 v2, v2, v41, s72
	v_mul_u32_u24_e32 v41, 0x540, v56
	s_waitcnt lgkmcnt(0)
	v_add_f32_e32 v29, v29, v40
	ds_bpermute_b32 v39, v39, v29
	s_waitcnt lgkmcnt(0)
	v_add_f32_e32 v29, v29, v39
	v_lshlrev_b32_e32 v39, 1, v55
	v_add_u32_e32 v40, v57, v39
	v_mad_u32_u24 v42, v56, s0, v40
	ds_write_b16_d16_hi v42, v2
	v_bfe_u32 v2, v3, 16, 1
	s_movk_i32 s0, 0x150
	v_add3_u32 v2, v3, v2, s72
	v_mad_u32_u24 v59, v43, s0, v40
	ds_write_b16_d16_hi v59, v2
	v_bfe_u32 v2, v4, 16, 1
	v_add3_u32 v2, v4, v2, s72
	v_mad_u32_u24 v4, v43, s0, s0
	v_add_u32_e32 v60, v40, v4
	ds_write_b16_d16_hi v60, v2
	v_bfe_u32 v2, v5, 16, 1
	v_add3_u32 v2, v5, v2, s72
	v_mov_b32_e32 v5, 0x2a0
	v_mad_u32_u24 v5, v43, s0, v5
	v_add_u32_e32 v61, v40, v5
	ds_write_b16_d16_hi v61, v2
	v_bfe_u32 v2, v10, 16, 1
	v_add3_u32 v2, v10, v2, s72
	ds_write_b16_d16_hi v42, v2 offset:32
	v_bfe_u32 v2, v11, 16, 1
	v_add3_u32 v2, v11, v2, s72
	ds_write_b16_d16_hi v59, v2 offset:32
	v_bfe_u32 v2, v8, 16, 1
	v_add3_u32 v2, v8, v2, s72
	ds_write_b16_d16_hi v60, v2 offset:32
	v_bfe_u32 v2, v9, 16, 1
	v_add3_u32 v2, v9, v2, s72
	ds_write_b16_d16_hi v61, v2 offset:32
	v_bfe_u32 v2, v6, 16, 1
	v_add3_u32 v2, v6, v2, s72
	ds_write_b16_d16_hi v42, v2 offset:64
	v_bfe_u32 v2, v7, 16, 1
	v_add3_u32 v2, v7, v2, s72
	ds_write_b16_d16_hi v59, v2 offset:64
	v_bfe_u32 v2, v12, 16, 1
	v_add3_u32 v2, v12, v2, s72
	ds_write_b16_d16_hi v60, v2 offset:64
	v_bfe_u32 v2, v13, 16, 1
	v_add3_u32 v2, v13, v2, s72
	ds_write_b16_d16_hi v61, v2 offset:64
	v_bfe_u32 v2, v18, 16, 1
	v_add3_u32 v2, v18, v2, s72
	ds_write_b16_d16_hi v42, v2 offset:96
	v_bfe_u32 v2, v19, 16, 1
	v_add3_u32 v2, v19, v2, s72
	ds_write_b16_d16_hi v59, v2 offset:96
	v_bfe_u32 v2, v16, 16, 1
	v_add3_u32 v2, v16, v2, s72
	ds_write_b16_d16_hi v60, v2 offset:96
	v_bfe_u32 v2, v17, 16, 1
	v_add3_u32 v2, v17, v2, s72
	ds_write_b16_d16_hi v61, v2 offset:96
	v_bfe_u32 v2, v14, 16, 1
	v_add3_u32 v2, v14, v2, s72
	ds_write_b16_d16_hi v42, v2 offset:128
	v_bfe_u32 v2, v15, 16, 1
	v_add3_u32 v2, v15, v2, s72
	ds_write_b16_d16_hi v59, v2 offset:128
	v_bfe_u32 v2, v32, 16, 1
	v_add3_u32 v2, v32, v2, s72
	ds_write_b16_d16_hi v60, v2 offset:128
	v_bfe_u32 v2, v21, 16, 1
	v_add3_u32 v2, v21, v2, s72
	ds_write_b16_d16_hi v61, v2 offset:128
	v_bfe_u32 v2, v34, 16, 1
	v_add3_u32 v2, v34, v2, s72
	ds_write_b16_d16_hi v42, v2 offset:160
	v_bfe_u32 v2, v46, 16, 1
	v_add3_u32 v2, v46, v2, s72
	ds_write_b16_d16_hi v59, v2 offset:160
	v_bfe_u32 v2, v49, 16, 1
	v_add3_u32 v2, v49, v2, s72
	ds_write_b16_d16_hi v60, v2 offset:160
	v_bfe_u32 v2, v53, 16, 1
	v_add3_u32 v2, v53, v2, s72
	ds_write_b16_d16_hi v61, v2 offset:160
	v_bfe_u32 v2, v30, 16, 1
	v_add3_u32 v2, v30, v2, s72
	ds_write_b16_d16_hi v42, v2 offset:192
	v_bfe_u32 v2, v31, 16, 1
	v_add3_u32 v2, v31, v2, s72
	ds_write_b16_d16_hi v59, v2 offset:192
	v_bfe_u32 v2, v48, 16, 1
	v_add3_u32 v2, v48, v2, s72
	ds_write_b16_d16_hi v60, v2 offset:192
	v_bfe_u32 v2, v54, 16, 1
	v_add3_u32 v2, v54, v2, s72
	ds_write_b16_d16_hi v61, v2 offset:192
	v_bfe_u32 v2, v45, 16, 1
	v_add3_u32 v2, v45, v2, s72
	ds_write_b16_d16_hi v42, v2 offset:224
	v_bfe_u32 v2, v47, 16, 1
	v_add3_u32 v2, v47, v2, s72
	ds_write_b16_d16_hi v59, v2 offset:224
	v_bfe_u32 v2, v36, 16, 1
	v_add3_u32 v2, v36, v2, s72
	ds_write_b16_d16_hi v60, v2 offset:224
	v_bfe_u32 v2, v33, 16, 1
	v_add3_u32 v2, v33, v2, s72
	ds_write_b16_d16_hi v61, v2 offset:224
	v_bfe_u32 v2, v44, 16, 1
	v_add3_u32 v2, v44, v2, s72
	ds_write_b16_d16_hi v42, v2 offset:256
	v_bfe_u32 v2, v35, 16, 1
	v_add3_u32 v2, v35, v2, s72
	ds_write_b16_d16_hi v59, v2 offset:256
	v_bfe_u32 v2, v20, 16, 1
	v_add3_u32 v2, v20, v2, s72
	ds_write_b16_d16_hi v60, v2 offset:256
	v_bfe_u32 v2, v37, 16, 1
	v_add3_u32 v2, v37, v2, s72
	v_mul_u32_u24_e32 v3, 0x150, v43
	ds_write_b16_d16_hi v61, v2 offset:256
	v_add3_u32 v2, v57, v41, v39
	ds_write_b16 v2, v1 offset:288
	v_add3_u32 v2, v57, v3, v39
	ds_write_b16 v2, v1 offset:288
	v_add3_u32 v2, v57, v4, v39
	v_lshl_add_u32 v45, v56, 3, v58
	s_movk_i32 s0, 0x100
	ds_write_b16 v2, v1 offset:288
	v_add3_u32 v2, v57, v5, v39
	v_and_b32_e32 v46, 8, v50
	v_cmp_gt_i32_e32 vcc, s0, v45
	ds_write_b16 v2, v1 offset:288
	v_mul_u32_u24_e32 v2, 0x150, v55
	v_cndmask_b32_e32 v30, 0, v46, vcc
	s_waitcnt lgkmcnt(0)
; __device__ __forceinline__ float frcp(float x) { return __builtin_amdgcn_rcpf(x); }
; __device__ void swa_item(const Params& p, int item) {
;     ...
;   bf16x8 pf[5];
;   _Pragma("unroll") for (int kk = 0; kk < 5; ++kk) pf[kk] = *(const bf16x8*)(Pl + c * 168 + kk * 32 + q * 8);
;   asm volatile("s_waitcnt lgkmcnt(0)" ::: "memory");
;   float il[4];
;   _Pragma("unroll") for (int jj = 0; jj < 4; ++jj) il[jj] = frcp(ls[jj]);
;   bfu* Ow = Pl;
;   _Pragma("unroll") for (int dt = 0; dt < 8; ++dt) {
;     f32x4 a = (f32x4){0.f, 0.f, 0.f, 0.f};
;     _Pragma("unroll") for (int kk = 0; kk < 5; ++kk) {
;       const int k0_ = w * 16 + kk * 32 + q * 8; const int ch_ = k0_ >> 3;
;       const int chp_ = (ch_ < 32) ? (ch_ ^ (((dt * 16 + c) >> 3) & 15)) : ch_;
;       bf16x8 vf = *(const bf16x8*)(Vt + (dt * 16 + c) * 280 + chp_ * 8);
;       a = __builtin_amdgcn_mfma_f32_16x16x32_bf16(pf[kk], vf, a, 0, 0, 0);
;     }
;     _Pragma("unroll") for (int jj = 0; jj < 4; ++jj) Ow[(q * 4 + jj) * 136 + dt * 16 + c] = f2bf(a[jj] * il[jj]);
;   }
	v_add3_u32 v2, v57, v2, v52
	v_mad_u32_u24 v47, v55, s25, 0
	v_xor_b32_e32 v30, v30, v45
	ds_read_b128 v[18:21], v2
	ds_read_b128 v[14:17], v2 offset:64
	ds_read_b128 v[10:13], v2 offset:128
	ds_read_b128 v[6:9], v2 offset:192
	ds_read_b128 v[2:5], v2 offset:256
	s_waitcnt lgkmcnt(0)
	v_lshl_add_u32 v30, v30, 1, v47
	s_movk_i32 s0, 0xe0
	ds_read_b128 v[30:33], v30
	v_cmp_gt_i32_e64 s[0:1], s0, v45
	v_add_u32_e32 v48, 32, v45
	v_cmp_gt_i32_e64 s[38:39], s2, v45
	v_cndmask_b32_e64 v34, 0, v46, s[0:1]
	v_xor_b32_e32 v34, v34, v48
	v_lshl_add_u32 v34, v34, 1, v47
	ds_read_b128 v[34:37], v34
	s_waitcnt lgkmcnt(1)
	v_mfma_f32_16x16x32_bf16 v[30:33], v[18:21], v[30:33], 0
	v_add_u32_e32 v49, 64, v45
	s_movk_i32 s2, 0xa0
	v_cmp_gt_i32_e64 s[40:41], s2, v45
	s_waitcnt lgkmcnt(0)
	v_mfma_f32_16x16x32_bf16 v[30:33], v[14:17], v[34:37], v[30:33]
	v_cndmask_b32_e64 v34, 0, v46, s[38:39]
	v_xor_b32_e32 v34, v34, v49
	v_lshl_add_u32 v34, v34, 1, v47
	ds_read_b128 v[34:37], v34
	v_add_u32_e32 v50, 0x60, v45
	s_waitcnt lgkmcnt(0)
	v_mfma_f32_16x16x32_bf16 v[30:33], v[10:13], v[34:37], v[30:33]
	v_cndmask_b32_e64 v34, 0, v46, s[40:41]
	v_xor_b32_e32 v34, v34, v50
	v_lshl_add_u32 v34, v34, 1, v47
	ds_read_b128 v[34:37], v34
	s_movk_i32 s2, 0x80
	v_cmp_gt_i32_e64 s[42:43], s2, v45
	s_waitcnt lgkmcnt(0)
	v_mfma_f32_16x16x32_bf16 v[30:33], v[6:9], v[34:37], v[30:33]
	v_add_u32_e32 v52, 0x80, v45
	v_cndmask_b32_e64 v34, 0, v46, s[42:43]
	v_xor_b32_e32 v34, v34, v52
	v_lshl_add_u32 v34, v34, 1, v47
	ds_read_b128 v[34:37], v34
	v_rcp_f32_e32 v39, v26
	s_waitcnt lgkmcnt(0)
	v_mfma_f32_16x16x32_bf16 v[30:33], v[2:5], v[34:37], v[30:33]
	v_rcp_f32_e32 v41, v27
	s_movk_i32 s2, 0x440
	v_rcp_f32_e32 v42, v28
	s_nop 4
	v_mul_f32_e32 v30, v39, v30
	v_bfe_u32 v34, v30, 16, 1
	v_add3_u32 v30, v30, v34, s72
	v_mad_u32_u24 v53, v56, s2, v40
	ds_write_b16_d16_hi v53, v30
	v_mul_f32_e32 v30, v41, v31
	v_bfe_u32 v31, v30, 16, 1
	v_rcp_f32_e32 v44, v29
	v_add3_u32 v30, v30, v31, s72
	v_mad_u32_u24 v40, v43, s3, v40
	ds_write_b16_d16_hi v40, v30
	v_mul_f32_e32 v30, v42, v32
	v_bfe_u32 v31, v30, 16, 1
	v_add3_u32 v30, v30, v31, s72
	ds_write_b16_d16_hi v40, v30 offset:272
	v_mul_f32_e32 v30, v44, v33
	v_bfe_u32 v31, v30, 16, 1
	v_add3_u32 v30, v30, v31, s72
	v_or_b32_e32 v43, 16, v46
	ds_write_b16_d16_hi v40, v30 offset:544
	v_cndmask_b32_e32 v30, 0, v43, vcc
	v_xor_b32_e32 v30, v30, v45
	v_lshl_add_u32 v30, v30, 1, v47
	ds_read_b128 v[30:33], v30 offset:8960
	v_cndmask_b32_e64 v34, 0, v43, s[0:1]
	v_xor_b32_e32 v34, v34, v48
	v_lshl_add_u32 v34, v34, 1, v47
	ds_read_b128 v[34:37], v34 offset:8960
	s_waitcnt lgkmcnt(1)
	v_mfma_f32_16x16x32_bf16 v[30:33], v[18:21], v[30:33], 0
	s_waitcnt lgkmcnt(0)
	v_mfma_f32_16x16x32_bf16 v[30:33], v[14:17], v[34:37], v[30:33]
	v_cndmask_b32_e64 v34, 0, v43, s[38:39]
	v_xor_b32_e32 v34, v34, v49
	v_lshl_add_u32 v34, v34, 1, v47
	ds_read_b128 v[34:37], v34 offset:8960
	s_waitcnt lgkmcnt(0)
	v_mfma_f32_16x16x32_bf16 v[30:33], v[10:13], v[34:37], v[30:33]
	v_cndmask_b32_e64 v34, 0, v43, s[40:41]
	v_xor_b32_e32 v34, v34, v50
	v_lshl_add_u32 v34, v34, 1, v47
	ds_read_b128 v[34:37], v34 offset:8960
	s_waitcnt lgkmcnt(0)
	v_mfma_f32_16x16x32_bf16 v[30:33], v[6:9], v[34:37], v[30:33]
	v_cndmask_b32_e64 v34, 0, v43, s[42:43]
	v_xor_b32_e32 v34, v34, v52
	v_lshl_add_u32 v34, v34, 1, v47
	ds_read_b128 v[34:37], v34 offset:8960
	v_or_b32_e32 v43, 32, v46
	s_waitcnt lgkmcnt(0)
	v_mfma_f32_16x16x32_bf16 v[30:33], v[2:5], v[34:37], v[30:33]
	s_nop 7
	v_mul_f32_e32 v30, v39, v30
	v_bfe_u32 v34, v30, 16, 1
	v_add3_u32 v30, v30, v34, s72
	ds_write_b16_d16_hi v53, v30 offset:32
	v_mul_f32_e32 v30, v41, v31
	v_bfe_u32 v31, v30, 16, 1
	v_add3_u32 v30, v30, v31, s72
	ds_write_b16_d16_hi v40, v30 offset:32
	v_mul_f32_e32 v30, v42, v32
	v_bfe_u32 v31, v30, 16, 1
	v_add3_u32 v30, v30, v31, s72
	ds_write_b16_d16_hi v40, v30 offset:304
	v_mul_f32_e32 v30, v44, v33
	v_bfe_u32 v31, v30, 16, 1
	v_add3_u32 v30, v30, v31, s72
	ds_write_b16_d16_hi v40, v30 offset:576
	v_cndmask_b32_e32 v30, 0, v43, vcc
	v_xor_b32_e32 v30, v30, v45
	v_lshl_add_u32 v30, v30, 1, v47
	ds_read_b128 v[30:33], v30 offset:17920
	v_cndmask_b32_e64 v34, 0, v43, s[0:1]
	v_xor_b32_e32 v34, v34, v48
	v_lshl_add_u32 v34, v34, 1, v47
	ds_read_b128 v[34:37], v34 offset:17920
	s_waitcnt lgkmcnt(1)
	v_mfma_f32_16x16x32_bf16 v[30:33], v[18:21], v[30:33], 0
	s_waitcnt lgkmcnt(0)
	v_mfma_f32_16x16x32_bf16 v[30:33], v[14:17], v[34:37], v[30:33]
	v_cndmask_b32_e64 v34, 0, v43, s[38:39]
	v_xor_b32_e32 v34, v34, v49
	v_lshl_add_u32 v34, v34, 1, v47
	ds_read_b128 v[34:37], v34 offset:17920
	s_waitcnt lgkmcnt(0)
	v_mfma_f32_16x16x32_bf16 v[30:33], v[10:13], v[34:37], v[30:33]
	v_cndmask_b32_e64 v34, 0, v43, s[40:41]
	v_xor_b32_e32 v34, v34, v50
	v_lshl_add_u32 v34, v34, 1, v47
	ds_read_b128 v[34:37], v34 offset:17920
	s_waitcnt lgkmcnt(0)
	v_mfma_f32_16x16x32_bf16 v[30:33], v[6:9], v[34:37], v[30:33]
	v_cndmask_b32_e64 v34, 0, v43, s[42:43]
	v_xor_b32_e32 v34, v34, v52
	v_lshl_add_u32 v34, v34, 1, v47
	ds_read_b128 v[34:37], v34 offset:17920
	v_or_b32_e32 v43, 48, v46
	s_waitcnt lgkmcnt(0)
	v_mfma_f32_16x16x32_bf16 v[30:33], v[2:5], v[34:37], v[30:33]
	s_nop 7
	v_mul_f32_e32 v30, v39, v30
	v_bfe_u32 v34, v30, 16, 1
	v_add3_u32 v30, v30, v34, s72
	ds_write_b16_d16_hi v53, v30 offset:64
	v_mul_f32_e32 v30, v41, v31
	v_bfe_u32 v31, v30, 16, 1
	v_add3_u32 v30, v30, v31, s72
	ds_write_b16_d16_hi v40, v30 offset:64
	v_mul_f32_e32 v30, v42, v32
	v_bfe_u32 v31, v30, 16, 1
	v_add3_u32 v30, v30, v31, s72
	ds_write_b16_d16_hi v40, v30 offset:336
	v_mul_f32_e32 v30, v44, v33
	v_bfe_u32 v31, v30, 16, 1
	v_add3_u32 v30, v30, v31, s72
	ds_write_b16_d16_hi v40, v30 offset:608
	v_cndmask_b32_e32 v30, 0, v43, vcc
	v_xor_b32_e32 v30, v30, v45
	v_lshl_add_u32 v30, v30, 1, v47
	ds_read_b128 v[30:33], v30 offset:26880
	v_cndmask_b32_e64 v34, 0, v43, s[0:1]
	v_xor_b32_e32 v34, v34, v48
	v_lshl_add_u32 v34, v34, 1, v47
	ds_read_b128 v[34:37], v34 offset:26880
	s_waitcnt lgkmcnt(1)
; __device__ void swa_item(const Params& p, int item) {
;     ...
;   _Pragma("unroll") for (int dt = 0; dt < 8; ++dt) {
;     f32x4 a = (f32x4){0.f, 0.f, 0.f, 0.f};
;     _Pragma("unroll") for (int kk = 0; kk < 5; ++kk) {
;       const int k0_ = w * 16 + kk * 32 + q * 8; const int ch_ = k0_ >> 3;
;       const int chp_ = (ch_ < 32) ? (ch_ ^ (((dt * 16 + c) >> 3) & 15)) : ch_;
;       bf16x8 vf = *(const bf16x8*)(Vt + (dt * 16 + c) * 280 + chp_ * 8);
;       a = __builtin_amdgcn_mfma_f32_16x16x32_bf16(pf[kk], vf, a, 0, 0, 0);
;     }
;     _Pragma("unroll") for (int jj = 0; jj < 4; ++jj) Ow[(q * 4 + jj) * 136 + dt * 16 + c] = f2bf(a[jj] * il[jj]);
;   }
	v_mfma_f32_16x16x32_bf16 v[30:33], v[18:21], v[30:33], 0
	s_waitcnt lgkmcnt(0)
	v_mfma_f32_16x16x32_bf16 v[30:33], v[14:17], v[34:37], v[30:33]
	v_cndmask_b32_e64 v34, 0, v43, s[38:39]
	v_xor_b32_e32 v34, v34, v49
	v_lshl_add_u32 v34, v34, 1, v47
	ds_read_b128 v[34:37], v34 offset:26880
	s_waitcnt lgkmcnt(0)
	v_mfma_f32_16x16x32_bf16 v[30:33], v[10:13], v[34:37], v[30:33]
	v_cndmask_b32_e64 v34, 0, v43, s[40:41]
	v_xor_b32_e32 v34, v34, v50
	v_lshl_add_u32 v34, v34, 1, v47
	ds_read_b128 v[34:37], v34 offset:26880
	s_waitcnt lgkmcnt(0)
	v_mfma_f32_16x16x32_bf16 v[30:33], v[6:9], v[34:37], v[30:33]
	v_cndmask_b32_e64 v34, 0, v43, s[42:43]
	v_xor_b32_e32 v34, v34, v52
	v_lshl_add_u32 v34, v34, 1, v47
	ds_read_b128 v[34:37], v34 offset:26880
	v_or_b32_e32 v43, 64, v46
	s_waitcnt lgkmcnt(0)
	v_mfma_f32_16x16x32_bf16 v[30:33], v[2:5], v[34:37], v[30:33]
	s_nop 7
	v_mul_f32_e32 v30, v39, v30
	v_bfe_u32 v34, v30, 16, 1
	v_add3_u32 v30, v30, v34, s72
	ds_write_b16_d16_hi v53, v30 offset:96
	v_mul_f32_e32 v30, v41, v31
	v_bfe_u32 v31, v30, 16, 1
	v_add3_u32 v30, v30, v31, s72
	ds_write_b16_d16_hi v40, v30 offset:96
	v_mul_f32_e32 v30, v42, v32
	v_bfe_u32 v31, v30, 16, 1
	v_add3_u32 v30, v30, v31, s72
	ds_write_b16_d16_hi v40, v30 offset:368
	v_mul_f32_e32 v30, v44, v33
	v_bfe_u32 v31, v30, 16, 1
	v_add3_u32 v30, v30, v31, s72
	ds_write_b16_d16_hi v40, v30 offset:640
	v_cndmask_b32_e32 v30, 0, v43, vcc
	v_xor_b32_e32 v30, v30, v45
	v_lshl_add_u32 v30, v30, 1, v47
	ds_read_b128 v[30:33], v30 offset:35840
	v_cndmask_b32_e64 v34, 0, v43, s[0:1]
	v_xor_b32_e32 v34, v34, v48
	v_lshl_add_u32 v34, v34, 1, v47
	ds_read_b128 v[34:37], v34 offset:35840
	s_waitcnt lgkmcnt(1)
	v_mfma_f32_16x16x32_bf16 v[30:33], v[18:21], v[30:33], 0
	s_waitcnt lgkmcnt(0)
	v_mfma_f32_16x16x32_bf16 v[30:33], v[14:17], v[34:37], v[30:33]
	v_cndmask_b32_e64 v34, 0, v43, s[38:39]
	v_xor_b32_e32 v34, v34, v49
	v_lshl_add_u32 v34, v34, 1, v47
	ds_read_b128 v[34:37], v34 offset:35840
	s_waitcnt lgkmcnt(0)
	v_mfma_f32_16x16x32_bf16 v[30:33], v[10:13], v[34:37], v[30:33]
	v_cndmask_b32_e64 v34, 0, v43, s[40:41]
	v_xor_b32_e32 v34, v34, v50
	v_lshl_add_u32 v34, v34, 1, v47
	ds_read_b128 v[34:37], v34 offset:35840
	s_waitcnt lgkmcnt(0)
	v_mfma_f32_16x16x32_bf16 v[30:33], v[6:9], v[34:37], v[30:33]
	v_cndmask_b32_e64 v34, 0, v43, s[42:43]
	v_xor_b32_e32 v34, v34, v52
	v_lshl_add_u32 v34, v34, 1, v47
	ds_read_b128 v[34:37], v34 offset:35840
	v_or_b32_e32 v43, 0x50, v46
	s_waitcnt lgkmcnt(0)
	v_mfma_f32_16x16x32_bf16 v[30:33], v[2:5], v[34:37], v[30:33]
	s_nop 7
	v_mul_f32_e32 v30, v39, v30
	v_bfe_u32 v34, v30, 16, 1
	v_add3_u32 v30, v30, v34, s72
	ds_write_b16_d16_hi v53, v30 offset:128
	v_mul_f32_e32 v30, v41, v31
	v_bfe_u32 v31, v30, 16, 1
	v_add3_u32 v30, v30, v31, s72
	ds_write_b16_d16_hi v40, v30 offset:128
	v_mul_f32_e32 v30, v42, v32
	v_bfe_u32 v31, v30, 16, 1
	v_add3_u32 v30, v30, v31, s72
	ds_write_b16_d16_hi v40, v30 offset:400
	v_mul_f32_e32 v30, v44, v33
	v_bfe_u32 v31, v30, 16, 1
	v_add3_u32 v30, v30, v31, s72
	ds_write_b16_d16_hi v40, v30 offset:672
	v_cndmask_b32_e32 v30, 0, v43, vcc
	v_xor_b32_e32 v30, v30, v45
	v_lshl_add_u32 v30, v30, 1, v47
	ds_read_b128 v[30:33], v30 offset:44800
	v_cndmask_b32_e64 v34, 0, v43, s[0:1]
	v_xor_b32_e32 v34, v34, v48
	v_lshl_add_u32 v34, v34, 1, v47
	ds_read_b128 v[34:37], v34 offset:44800
	s_waitcnt lgkmcnt(1)
	v_mfma_f32_16x16x32_bf16 v[30:33], v[18:21], v[30:33], 0
	s_waitcnt lgkmcnt(0)
	v_mfma_f32_16x16x32_bf16 v[30:33], v[14:17], v[34:37], v[30:33]
	v_cndmask_b32_e64 v34, 0, v43, s[38:39]
	v_xor_b32_e32 v34, v34, v49
	v_lshl_add_u32 v34, v34, 1, v47
	ds_read_b128 v[34:37], v34 offset:44800
	s_waitcnt lgkmcnt(0)
	v_mfma_f32_16x16x32_bf16 v[30:33], v[10:13], v[34:37], v[30:33]
	v_cndmask_b32_e64 v34, 0, v43, s[40:41]
	v_xor_b32_e32 v34, v34, v50
	v_lshl_add_u32 v34, v34, 1, v47
	ds_read_b128 v[34:37], v34 offset:44800
	s_waitcnt lgkmcnt(0)
	v_mfma_f32_16x16x32_bf16 v[30:33], v[6:9], v[34:37], v[30:33]
	v_cndmask_b32_e64 v34, 0, v43, s[42:43]
	v_xor_b32_e32 v34, v34, v52
	v_lshl_add_u32 v34, v34, 1, v47
	ds_read_b128 v[34:37], v34 offset:44800
	v_or_b32_e32 v43, 0x60, v46
	s_waitcnt lgkmcnt(0)
	v_mfma_f32_16x16x32_bf16 v[30:33], v[2:5], v[34:37], v[30:33]
	s_nop 7
	v_mul_f32_e32 v30, v39, v30
	v_bfe_u32 v34, v30, 16, 1
	v_add3_u32 v30, v30, v34, s72
	ds_write_b16_d16_hi v53, v30 offset:160
	v_mul_f32_e32 v30, v41, v31
	v_bfe_u32 v31, v30, 16, 1
	v_add3_u32 v30, v30, v31, s72
	ds_write_b16_d16_hi v40, v30 offset:160
	v_mul_f32_e32 v30, v42, v32
	v_bfe_u32 v31, v30, 16, 1
	v_add3_u32 v30, v30, v31, s72
	ds_write_b16_d16_hi v40, v30 offset:432
	v_mul_f32_e32 v30, v44, v33
	v_bfe_u32 v31, v30, 16, 1
	v_add3_u32 v30, v30, v31, s72
	ds_write_b16_d16_hi v40, v30 offset:704
	v_cndmask_b32_e32 v30, 0, v43, vcc
	v_xor_b32_e32 v30, v30, v45
	v_lshl_add_u32 v30, v30, 1, v47
	ds_read_b128 v[30:33], v30 offset:53760
	v_cndmask_b32_e64 v34, 0, v43, s[0:1]
	v_xor_b32_e32 v34, v34, v48
	v_lshl_add_u32 v34, v34, 1, v47
	ds_read_b128 v[34:37], v34 offset:53760
	s_waitcnt lgkmcnt(1)
	v_mfma_f32_16x16x32_bf16 v[30:33], v[18:21], v[30:33], 0
	s_waitcnt lgkmcnt(0)
	v_mfma_f32_16x16x32_bf16 v[30:33], v[14:17], v[34:37], v[30:33]
	v_cndmask_b32_e64 v34, 0, v43, s[38:39]
	v_xor_b32_e32 v34, v34, v49
	v_lshl_add_u32 v34, v34, 1, v47
	ds_read_b128 v[34:37], v34 offset:53760
	s_waitcnt lgkmcnt(0)
	v_mfma_f32_16x16x32_bf16 v[30:33], v[10:13], v[34:37], v[30:33]
	v_cndmask_b32_e64 v34, 0, v43, s[40:41]
	v_xor_b32_e32 v34, v34, v50
	v_lshl_add_u32 v34, v34, 1, v47
	ds_read_b128 v[34:37], v34 offset:53760
	s_waitcnt lgkmcnt(0)
; __device__ __forceinline__ float flog(float x) { return __builtin_amdgcn_logf(x) * 0.6931471805599453f; }
; __device__ void swa_item(const Params& p, int item) {
;     ...
;   _Pragma("unroll") for (int dt = 0; dt < 8; ++dt) {
;     f32x4 a = (f32x4){0.f, 0.f, 0.f, 0.f};
;     _Pragma("unroll") for (int kk = 0; kk < 5; ++kk) {
;       const int k0_ = w * 16 + kk * 32 + q * 8; const int ch_ = k0_ >> 3;
;       const int chp_ = (ch_ < 32) ? (ch_ ^ (((dt * 16 + c) >> 3) & 15)) : ch_;
;       bf16x8 vf = *(const bf16x8*)(Vt + (dt * 16 + c) * 280 + chp_ * 8);
;       a = __builtin_amdgcn_mfma_f32_16x16x32_bf16(pf[kk], vf, a, 0, 0, 0);
;     }
;     _Pragma("unroll") for (int jj = 0; jj < 4; ++jj) Ow[(q * 4 + jj) * 136 + dt * 16 + c] = f2bf(a[jj] * il[jj]);
;   }
;   asm volatile("s_waitcnt lgkmcnt(0)" ::: "memory");
;   _Pragma("unroll") for (int i = 0; i < 4; ++i) {
;     const int id = lane + 64 * i; const int rr = id >> 4, c8 = id & 15;
;     long orow = rowb + (long)(qb * 128 + w * 16 + rr) * dil + r;
;     *(bf16x8*)(buf + orow * 4608 + qcol + c8 * 8) = *(const bf16x8*)(Ow + rr * 136 + c8 * 8);
;   }
;   if (c == 0) {
;     _Pragma("unroll") for (int jj = 0; jj < 4; ++jj) {
;       long orow = rowb + (long)(qb * 128 + w * 16 + q * 4 + jj) * dil + r;
;       misc[MF_LSE + ((long)pat * MTOK + orow) * 4 + head] = mx[jj] + flog(ls[jj]);
;     }
;   }
	v_mfma_f32_16x16x32_bf16 v[30:33], v[6:9], v[34:37], v[30:33]
	v_cndmask_b32_e64 v34, 0, v43, s[42:43]
	v_xor_b32_e32 v34, v34, v52
	v_lshl_add_u32 v34, v34, 1, v47
	ds_read_b128 v[34:37], v34 offset:53760
	s_waitcnt lgkmcnt(0)
	v_mfma_f32_16x16x32_bf16 v[30:33], v[2:5], v[34:37], v[30:33]
	s_nop 7
	v_mul_f32_e32 v30, v39, v30
	v_bfe_u32 v34, v30, 16, 1
	v_add3_u32 v30, v30, v34, s72
	ds_write_b16_d16_hi v53, v30 offset:192
	v_mul_f32_e32 v30, v41, v31
	v_bfe_u32 v31, v30, 16, 1
	v_add3_u32 v30, v30, v31, s72
	ds_write_b16_d16_hi v40, v30 offset:192
	v_mul_f32_e32 v30, v42, v32
	v_bfe_u32 v31, v30, 16, 1
	v_add3_u32 v30, v30, v31, s72
	ds_write_b16_d16_hi v40, v30 offset:464
	v_mul_f32_e32 v30, v44, v33
	v_bfe_u32 v31, v30, 16, 1
	v_add3_u32 v30, v30, v31, s72
	v_or_b32_e32 v34, 0x70, v46
	ds_write_b16_d16_hi v40, v30 offset:736
	v_cndmask_b32_e32 v30, 0, v34, vcc
	v_xor_b32_e32 v30, v30, v45
	v_lshl_add_u32 v30, v30, 1, v47
	ds_read_b128 v[30:33], v30 offset:62720
	v_cmp_eq_u32_e32 vcc, 0, v55
	s_waitcnt lgkmcnt(0)
	v_mfma_f32_16x16x32_bf16 v[18:21], v[18:21], v[30:33], 0
	v_cndmask_b32_e64 v30, 0, v34, s[0:1]
	v_xor_b32_e32 v30, v30, v48
	v_lshl_add_u32 v30, v30, 1, v47
	ds_read_b128 v[30:33], v30 offset:62720
	s_waitcnt lgkmcnt(0)
	v_mfma_f32_16x16x32_bf16 v[14:17], v[14:17], v[30:33], v[18:21]
	s_nop 2
	v_cndmask_b32_e64 v18, 0, v34, s[38:39]
	v_xor_b32_e32 v18, v18, v49
	v_lshl_add_u32 v18, v18, 1, v47
	ds_read_b128 v[18:21], v18 offset:62720
	s_waitcnt lgkmcnt(0)
	v_mfma_f32_16x16x32_bf16 v[10:13], v[10:13], v[18:21], v[14:17]
	s_nop 2
	v_cndmask_b32_e64 v14, 0, v34, s[40:41]
	v_xor_b32_e32 v14, v14, v50
	v_lshl_add_u32 v14, v14, 1, v47
	ds_read_b128 v[14:17], v14 offset:62720
	s_waitcnt lgkmcnt(0)
	v_mfma_f32_16x16x32_bf16 v[6:9], v[6:9], v[14:17], v[10:13]
	s_nop 2
	v_cndmask_b32_e64 v10, 0, v34, s[42:43]
	v_xor_b32_e32 v10, v10, v52
	v_lshl_add_u32 v10, v10, 1, v47
	ds_read_b128 v[10:13], v10 offset:62720
	s_waitcnt lgkmcnt(0)
	v_mfma_f32_16x16x32_bf16 v[2:5], v[2:5], v[10:13], v[6:9]
	s_nop 2
	v_or_b32_e32 v8, v51, v56
	v_ashrrev_i32_e32 v9, 31, v8
	s_nop 2
	v_mul_f32_e32 v2, v39, v2
	v_bfe_u32 v6, v2, 16, 1
	v_add3_u32 v2, v2, v6, s72
	ds_write_b16_d16_hi v53, v2 offset:224
	v_mul_f32_e32 v2, v41, v3
	v_bfe_u32 v3, v2, 16, 1
	v_add3_u32 v2, v2, v3, s72
	ds_write_b16_d16_hi v40, v2 offset:224
	v_mul_f32_e32 v2, v42, v4
	v_bfe_u32 v3, v2, 16, 1
	v_add3_u32 v2, v2, v3, s72
	ds_write_b16_d16_hi v40, v2 offset:496
	v_mul_f32_e32 v2, v44, v5
	v_bfe_u32 v3, v2, 16, 1
	v_add3_u32 v2, v2, v3, s72
	ds_write_b16_d16_hi v40, v2 offset:768
	v_lshlrev_b64 v[2:3], s22, v[8:9]
	v_lshl_add_u64 v[10:11], v[2:3], 0, s[26:27]
	v_mul_u32_u24_e32 v2, 0x110, v56
	s_waitcnt lgkmcnt(0)
	v_lshl_add_u64 v[6:7], s[52:53], 0, v[0:1]
	v_add3_u32 v0, v57, v0, v2
	ds_read_b128 v[2:5], v0
	v_mad_u64_u32 v[12:13], s[0:1], v10, s89, v[6:7]
	v_mad_i32_i24 v13, v11, s89, v13
	s_waitcnt lgkmcnt(0)
	global_store_dwordx4 v[12:13], v[2:5], off
	s_nop 1
	v_or_b32_e32 v2, 4, v8
	v_ashrrev_i32_e32 v3, 31, v2
	v_lshlrev_b64 v[2:3], s22, v[2:3]
	v_lshl_add_u64 v[10:11], v[2:3], 0, s[26:27]
	ds_read_b128 v[2:5], v0 offset:1088
	v_mad_u64_u32 v[12:13], s[0:1], v10, s89, v[6:7]
	v_mad_i32_i24 v13, v11, s89, v13
	s_waitcnt lgkmcnt(0)
	global_store_dwordx4 v[12:13], v[2:5], off
	s_nop 1
	v_or_b32_e32 v2, 8, v8
	v_ashrrev_i32_e32 v3, 31, v2
	v_lshlrev_b64 v[2:3], s22, v[2:3]
	v_lshl_add_u64 v[10:11], v[2:3], 0, s[26:27]
	ds_read_b128 v[2:5], v0 offset:2176
	v_mad_u64_u32 v[12:13], s[0:1], v10, s89, v[6:7]
	v_mad_i32_i24 v13, v11, s89, v13
	s_waitcnt lgkmcnt(0)
	global_store_dwordx4 v[12:13], v[2:5], off
	s_nop 1
	v_or_b32_e32 v2, 12, v8
	v_ashrrev_i32_e32 v3, 31, v2
	v_lshlrev_b64 v[2:3], s22, v[2:3]
	v_lshl_add_u64 v[8:9], v[2:3], 0, s[26:27]
	ds_read_b128 v[2:5], v0 offset:3264
	v_mad_u64_u32 v[6:7], s[0:1], v8, s89, v[6:7]
	v_mad_i32_i24 v7, v9, s89, v7
	s_waitcnt lgkmcnt(0)
	global_store_dwordx4 v[6:7], v[2:5], off
	s_and_saveexec_b64 s[0:1], vcc
	s_cbranch_execz .LBB0_101
	s_ashr_i32 s89, s88, 31
	s_lshl_b64 s[2:3], s[88:89], 19
	v_readlane_b32 s12, v252, 20
	v_log_f32_e32 v0, v26
	s_add_u32 s2, s12, s2
	v_readlane_b32 s12, v252, 21
	v_or_b32_e32 v2, v51, v38
	s_addc_u32 s3, s12, s3
	s_lshl_b32 s12, s23, 2
	s_add_u32 s2, s2, s12
	v_ashrrev_i32_e32 v3, 31, v2
	v_readlane_b32 s12, v254, 13
	v_lshlrev_b64 v[4:5], s22, v[2:3]
	v_readlane_b32 s13, v254, 14
	v_fmac_f32_e32 v22, 0x3f317218, v0
	v_log_f32_e32 v0, v27
	s_addc_u32 s3, s3, 0
	v_lshl_add_u64 v[4:5], v[4:5], 0, s[12:13]
	v_lshl_add_u64 v[4:5], v[4:5], 4, s[2:3]
	global_store_dword v[4:5], v22, off
	v_or_b32_e32 v4, 1, v2
	v_ashrrev_i32_e32 v5, 31, v4
	v_fmac_f32_e32 v23, 0x3f317218, v0
	v_log_f32_e32 v0, v28
	v_lshlrev_b64 v[4:5], s22, v[4:5]
	v_lshl_add_u64 v[4:5], v[4:5], 0, s[12:13]
	v_lshl_add_u64 v[4:5], v[4:5], 4, s[2:3]
	global_store_dword v[4:5], v23, off
	v_or_b32_e32 v4, 2, v2
	v_fmac_f32_e32 v24, 0x3f317218, v0
	v_or_b32_e32 v2, 3, v2
	v_log_f32_e32 v0, v29
	v_ashrrev_i32_e32 v5, 31, v4
	v_ashrrev_i32_e32 v3, 31, v2
	v_lshlrev_b64 v[4:5], s22, v[4:5]
	v_lshlrev_b64 v[2:3], s22, v[2:3]
	v_lshl_add_u64 v[4:5], v[4:5], 0, s[12:13]
	v_lshl_add_u64 v[2:3], v[2:3], 0, s[12:13]
	s_movk_i32 s89, 0x2400
	v_lshl_add_u64 v[4:5], v[4:5], 4, s[2:3]
	v_fmac_f32_e32 v25, 0x3f317218, v0
	v_lshl_add_u64 v[2:3], v[2:3], 4, s[2:3]
	global_store_dword v[4:5], v24, off
	global_store_dword v[2:3], v25, off
	s_branch .LBB0_101
